# HGRN/GLA f32 gate rows staged by LDS-DMA into a 4-chunk LDS ring (no VGPR staging / ds_write for them)
# speedup vs baseline: 1.0081x; 1.0013x over previous
.Lls2_8_entry:
	v_and_b32_e32 v82, 63, v196
	v_and_b32_e32 v83, 7, v82
	v_lshrrev_b32_e32 v84, 3, v82
	s_min_u32 s29, s0, 4
	s_mul_i32 s29, s29, 0x5600
	v_and_b32_e32 v85, 3, v83
	v_cmp_eq_u32_e64 s[6:7], 1, v85
	v_cmp_eq_u32_e64 s[8:9], 2, v85
	v_cmp_eq_u32_e64 s[10:11], 3, v85
	v_lshl_add_u32 v0, v83, 5, s29
	v_lshl_add_u32 v1, v84, 2, s29
	s_lshl_b32 s37, s16, 11
	v_lshrrev_b32_e32 v83, 3, v82
	v_and_b32_e32 v84, 7, v82
	v_add_u32_e32 v85, s37, v83
	s_lshl_b32 s21, s17, 7
	s_add_u32 s21, s21, 0x10800500
	v_mul_u32_u24_e32 v5, 0xd00, v85
	v_lshl_add_u32 v5, v84, 4, v5
	v_add_u32_e32 v5, s21, v5
	v_lshlrev_b32_e32 v2, 8, v83
	v_lshl_add_u32 v2, v84, 5, v2
	v_add_u32_e32 v2, s29, v2
	s_lshl_b32 s21, s17, 8
	s_add_u32 s21, s21, 0x13e00200
	v_lshrrev_b32_e32 v8, 4, v82
	v_add_u32_e32 v8, s37, v8
	v_mul_u32_u24_e32 v8, 0x630, v8
	v_and_b32_e32 v88, 15, v82
	v_lshl_add_u32 v8, v88, 4, v8
	v_add_u32_e32 v8, s21, v8
	v_add_u32_e32 v88, 0x18c0, v8
	v_lshrrev_b32_e32 v84, 3, v82
	v_and_b32_e32 v83, 7, v82
	v_add_u32_e32 v85, s37, v84
	s_lshl_b32 s22, s14, 3
	s_lshl_b32 s21, s17, 6
	s_add_u32 s21, s21, s22
	s_lshl_b32 s44, s21, 1
	s_add_u32 s44, s44, 0x8401220
	v_lshlrev_b32_e32 v6, 13, v85
	v_lshlrev_b32_e32 v4, 5, v84
	v_lshl_add_u32 v4, v83, 2, v4
	v_lshl_add_u32 v6, v83, 1, v6
	v_add_u32_e32 v6, s44, v6
	v_add_u32_e32 v4, s29, v4
	v_and_b32_e32 v83, 7, v82
	v_lshrrev_b32_e32 v84, 3, v82
	v_add_u32_e32 v85, s37, v82
	v_lshlrev_b32_e32 v7, 11, v85
	s_lshl_b32 s44, s21, 1
	s_add_u32 s44, s44, 0x6300400
	v_add_u32_e32 v7, s44, v7
	s_lshl_b32 s44, s28, 3
	s_add_u32 s44, s44, s16
	s_lshl_b32 s44, s44, 2
	s_add_u32 s44, s44, s17
	s_mul_i32 s44, s44, 0x4000
	s_add_u32 s44, s44, 0x4380000
	s_lshl_b32 s24, s22, 2
	s_add_u32 s44, s44, s24
	v_lshlrev_b32_e32 v89, 11, v83
	v_lshl_add_u32 v89, v84, 2, v89
	v_add_u32_e32 v89, s44, v89
	v_readlane_b32 s26, v253, 29
	v_readlane_b32 s27, v253, 30
	v_lshlrev_b32_e32 v90, 4, v83
	v_lshl_add_u32 v90, v84, 1, v90
	v_add_u32_e32 v90, s29, v90
	v_lshl_add_u32 v91, v82, 4, s29
	v_lshl_add_u32 v96, v82, 2, s29
	v_lshl_add_u32 v90, v82, 1, s29
	v_subrev_u32_e32 v90, 0x200, v90
	v_lshrrev_b32_e32 v83, 3, v82
	v_and_b32_e32 v84, 7, v82
	v_lshlrev_b32_e32 v85, 8, v83
	v_lshl_add_u32 v85, v84, 5, v85
	v_add_u32_e32 v85, s29, v85
	v_bfe_u32 v83, v83, 1, 1
	v_xor_b32_e32 v84, 0, v83
	v_lshl_add_u32 v97, v84, 4, v85
	v_xor_b32_e32 v84, 1, v83
	v_lshl_add_u32 v98, v84, 4, v85
	v_mov_b32_e32 v10, 0
	v_mov_b32_e32 v11, 0
	v_mov_b32_e32 v12, 0
	v_mov_b32_e32 v13, 0
	v_mov_b32_e32 v14, 0
	v_mov_b32_e32 v15, 0
	v_mov_b32_e32 v16, 0
	v_mov_b32_e32 v17, 0
	v_mov_b32_e32 v9, 0
	v_mov_b32_e32 v18, 0
	v_mov_b32_e32 v19, 0
	v_mov_b32_e32 v20, 0
	v_mov_b32_e32 v86, 0
	v_mov_b32_e32 v87, 0
	s_setprio 2
	s_movk_i32 s12, 64
	s_nop 0
	global_load_dwordx4 v[62:65], v5, s[94:95]
	global_load_ushort v23, v6, s[94:95]
	v_add_u32_e32 v5, 0x6800, v5
	v_add_u32_e32 v6, 0x10000, v6
	s_waitcnt vmcnt(0)
	s_waitcnt vmcnt(1)
	v_lshlrev_b32_e32 v78, 16, v62
	v_and_b32_e32 v79, 0xffff0000, v62
	v_lshlrev_b32_e32 v80, 16, v63
	v_and_b32_e32 v81, 0xffff0000, v63
	ds_write_b128 v2, v[78:81] offset:0
	v_lshlrev_b32_e32 v82, 16, v64
	v_and_b32_e32 v83, 0xffff0000, v64
	v_lshlrev_b32_e32 v84, 16, v65
	v_and_b32_e32 v85, 0xffff0000, v65
	ds_write_b128 v2, v[82:85] offset:16
	s_waitcnt vmcnt(0)
	v_lshlrev_b32_e32 v23, 16, v23
	s_nop 0
	ds_write_b32 v4, v23 offset:2048
	global_load_dwordx4 v[66:69], v5, s[94:95]
	global_load_ushort v33, v6, s[94:95]
	v_add_u32_e32 v5, 0x6800, v5
	v_add_u32_e32 v6, 0x10000, v6
	global_load_dwordx4 v[70:73], v5, s[94:95]
	global_load_ushort v35, v6, s[94:95]
	v_add_u32_e32 v5, 0x6800, v5
	v_add_u32_e32 v6, 0x10000, v6
	s_add_i32 m0, s29, 0x1200
	s_nop 0
	global_load_lds_dwordx4 v8, s[94:95]
	s_add_i32 m0, s29, 0x1600
	v_add_u32_e32 v8, 0x3180, v8
	global_load_lds_dwordx4 v88, s[94:95]
	v_add_u32_e32 v88, 0x3180, v88
	global_load_dwordx4 v[74:77], v5, s[94:95]
	global_load_ushort v36, v6, s[94:95]
	v_add_u32_e32 v5, 0x6800, v5
	v_add_u32_e32 v6, 0x10000, v6
	s_add_i32 m0, s29, 0x1a00
	s_nop 0
	global_load_lds_dwordx4 v8, s[94:95]
	s_add_i32 m0, s29, 0x1e00
	v_add_u32_e32 v8, 0x3180, v8
	global_load_lds_dwordx4 v88, s[94:95]
	v_add_u32_e32 v88, 0x3180, v88
	global_load_dwordx4 v[62:65], v5, s[94:95]
	global_load_ushort v23, v6, s[94:95]
	v_add_u32_e32 v5, 0x6800, v5
	v_add_u32_e32 v6, 0x10000, v6
	s_add_i32 m0, s29, 0x2200
	s_nop 0
	global_load_lds_dwordx4 v8, s[94:95]
	s_add_i32 m0, s29, 0x2600
	v_add_u32_e32 v8, 0x3180, v8
	global_load_lds_dwordx4 v88, s[94:95]
	v_add_u32_e32 v88, 0x3180, v88
	ds_read_b128 v[24:27], v0 offset:0
	ds_read_b128 v[28:31], v0 offset:16
	s_waitcnt vmcnt(8)
	ds_read_b128 v[46:49], v0 offset:4608
	ds_read_b128 v[50:53], v0 offset:4624
	ds_read_b32 v32, v1 offset:2048
.Lls2_8_loop:
	s_waitcnt lgkmcnt(0)
	ds_read_b128 v[38:41], v0 offset:256
	ds_read_b128 v[42:45], v0 offset:272
	ds_read_b128 v[54:57], v0 offset:4864
	ds_read_b128 v[58:61], v0 offset:4880
	ds_read_b32 v34, v1 offset:2080
	v_sub_f32_e32 v10, v10, v32
	v_sub_f32_e32 v11, v11, v32
	v_sub_f32_e32 v12, v12, v32
	s_waitcnt vmcnt(13)
	v_sub_f32_e32 v13, v13, v32
	v_sub_f32_e32 v14, v14, v32
	v_sub_f32_e32 v15, v15, v32
	v_lshlrev_b32_e32 v78, 16, v66
	v_sub_f32_e32 v16, v16, v32
	v_sub_f32_e32 v17, v17, v32
	v_fma_f32 v10, v46, v10, v32
	v_and_b32_e32 v79, 0xffff0000, v66
	v_fma_f32 v11, v47, v11, v32
	v_mul_f32_e32 v86, v24, v10
	v_fma_f32 v12, v48, v12, v32
	v_lshlrev_b32_e32 v80, 16, v67
	v_fmac_f32_e32 v86, v25, v11
	v_fma_f32 v13, v49, v13, v32
	v_fmac_f32_e32 v86, v26, v12
	v_fma_f32 v14, v50, v14, v32
	v_fmac_f32_e32 v86, v27, v13
	v_fma_f32 v15, v51, v15, v32
	v_fmac_f32_e32 v86, v28, v14
	v_fma_f32 v16, v52, v16, v32
	v_fmac_f32_e32 v86, v29, v15
	v_fma_f32 v17, v53, v17, v32
	v_fmac_f32_e32 v86, v30, v16
	v_fmac_f32_e32 v86, v31, v17
	ds_write_b32 v96, v86 offset:12800
	s_waitcnt lgkmcnt(1)
	ds_read_b128 v[24:27], v0 offset:512
	ds_read_b128 v[28:31], v0 offset:528
	ds_read_b128 v[46:49], v0 offset:5120
	ds_read_b128 v[50:53], v0 offset:5136
	ds_read_b32 v32, v1 offset:2112
	v_sub_f32_e32 v10, v10, v34
	v_sub_f32_e32 v11, v11, v34
	v_sub_f32_e32 v12, v12, v34
	v_and_b32_e32 v81, 0xffff0000, v67
	v_sub_f32_e32 v13, v13, v34
	v_sub_f32_e32 v14, v14, v34
	v_sub_f32_e32 v15, v15, v34
	ds_write_b128 v2, v[78:81] offset:2304
	v_sub_f32_e32 v16, v16, v34
	v_sub_f32_e32 v17, v17, v34
	v_fma_f32 v10, v54, v10, v34
	v_lshlrev_b32_e32 v82, 16, v68
	v_fma_f32 v11, v55, v11, v34
	v_mul_f32_e32 v87, v38, v10
	v_fma_f32 v12, v56, v12, v34
	v_and_b32_e32 v83, 0xffff0000, v68
	v_fmac_f32_e32 v87, v39, v11
	v_fma_f32 v13, v57, v13, v34
	v_fmac_f32_e32 v87, v40, v12
	v_fma_f32 v14, v58, v14, v34
	v_fmac_f32_e32 v87, v41, v13
	v_fma_f32 v15, v59, v15, v34
	v_fmac_f32_e32 v87, v42, v14
	v_fma_f32 v16, v60, v16, v34
	v_fmac_f32_e32 v87, v43, v15
	v_fma_f32 v17, v61, v17, v34
	v_fmac_f32_e32 v87, v44, v16
	v_fmac_f32_e32 v87, v45, v17
	ds_write_b32 v96, v87 offset:13056
	s_waitcnt lgkmcnt(2)
	ds_read_b128 v[38:41], v0 offset:768
	ds_read_b128 v[42:45], v0 offset:784
	ds_read_b128 v[54:57], v0 offset:5376
	ds_read_b128 v[58:61], v0 offset:5392
	ds_read_b32 v34, v1 offset:2144
	v_sub_f32_e32 v10, v10, v32
	v_sub_f32_e32 v11, v11, v32
	v_sub_f32_e32 v12, v12, v32
	v_lshlrev_b32_e32 v84, 16, v69
	v_sub_f32_e32 v13, v13, v32
	v_sub_f32_e32 v14, v14, v32
	v_sub_f32_e32 v15, v15, v32
	v_and_b32_e32 v85, 0xffff0000, v69
	v_sub_f32_e32 v16, v16, v32
	v_sub_f32_e32 v17, v17, v32
	v_fma_f32 v10, v46, v10, v32
	ds_write_b128 v2, v[82:85] offset:2320
	v_fma_f32 v11, v47, v11, v32
	v_mul_f32_e32 v86, v24, v10
	v_fma_f32 v12, v48, v12, v32
	s_waitcnt vmcnt(12)
	v_fmac_f32_e32 v86, v25, v11
	v_fma_f32 v13, v49, v13, v32
	v_fmac_f32_e32 v86, v26, v12
	v_fma_f32 v14, v50, v14, v32
	v_fmac_f32_e32 v86, v27, v13
	v_fma_f32 v15, v51, v15, v32
	v_fmac_f32_e32 v86, v28, v14
	v_fma_f32 v16, v52, v16, v32
	v_fmac_f32_e32 v86, v29, v15
	v_fma_f32 v17, v53, v17, v32
	v_fmac_f32_e32 v86, v30, v16
	v_fmac_f32_e32 v86, v31, v17
	ds_write_b32 v96, v86 offset:13312
	s_waitcnt lgkmcnt(2)
	ds_read_b128 v[24:27], v0 offset:1024
	ds_read_b128 v[28:31], v0 offset:1040
	ds_read_b128 v[46:49], v0 offset:5632
	ds_read_b128 v[50:53], v0 offset:5648
	ds_read_b32 v32, v1 offset:2176
	v_sub_f32_e32 v10, v10, v34
	v_sub_f32_e32 v11, v11, v34
	v_sub_f32_e32 v12, v12, v34
	v_lshlrev_b32_e32 v33, 16, v33
	v_sub_f32_e32 v13, v13, v34
	v_sub_f32_e32 v14, v14, v34
	v_sub_f32_e32 v15, v15, v34
	s_nop 0
	v_sub_f32_e32 v16, v16, v34
	v_sub_f32_e32 v17, v17, v34
	v_fma_f32 v10, v54, v10, v34
	ds_write_b32 v4, v33 offset:4352
	v_fma_f32 v11, v55, v11, v34
	v_mul_f32_e32 v87, v38, v10
	v_fma_f32 v12, v56, v12, v34
	v_fmac_f32_e32 v87, v39, v11
	v_fma_f32 v13, v57, v13, v34
	v_fmac_f32_e32 v87, v40, v12
	v_fma_f32 v14, v58, v14, v34
	v_fmac_f32_e32 v87, v41, v13
	v_fma_f32 v15, v59, v15, v34
	v_fmac_f32_e32 v87, v42, v14
	v_fma_f32 v16, v60, v16, v34
	v_fmac_f32_e32 v87, v43, v15
	v_fma_f32 v17, v61, v17, v34
	v_fmac_f32_e32 v87, v44, v16
	v_fmac_f32_e32 v87, v45, v17
	ds_write_b32 v96, v87 offset:13568
	s_waitcnt lgkmcnt(2)
	ds_read_b128 v[38:41], v0 offset:1280
	ds_read_b128 v[42:45], v0 offset:1296
	ds_read_b128 v[54:57], v0 offset:5888
	ds_read_b128 v[58:61], v0 offset:5904
	ds_read_b32 v34, v1 offset:2208
	v_sub_f32_e32 v10, v10, v32
	v_sub_f32_e32 v11, v11, v32
	v_sub_f32_e32 v12, v12, v32
	global_load_dwordx4 v[66:69], v5, s[94:95]
	global_load_ushort v33, v6, s[94:95]
	v_add_u32_e32 v5, 0x6800, v5
	v_add_u32_e32 v6, 0x10000, v6
	v_sub_f32_e32 v13, v13, v32
	v_sub_f32_e32 v14, v14, v32
	v_sub_f32_e32 v15, v15, v32
	s_add_i32 m0, s29, 0x2a00
	s_nop 0
	global_load_lds_dwordx4 v8, s[94:95]
	s_add_i32 m0, s29, 0x2e00
	v_add_u32_e32 v8, 0x3180, v8
	global_load_lds_dwordx4 v88, s[94:95]
	v_add_u32_e32 v88, 0x3180, v88
	v_sub_f32_e32 v16, v16, v32
	v_sub_f32_e32 v17, v17, v32
	v_fma_f32 v10, v46, v10, v32
	ds_read_b128 v[100:103], v97 offset:14848
	v_fma_f32 v11, v47, v11, v32
	v_mul_f32_e32 v86, v24, v10
	v_fma_f32 v12, v48, v12, v32
	ds_read_b128 v[104:107], v98 offset:14848
	v_fmac_f32_e32 v86, v25, v11
	v_fma_f32 v13, v49, v13, v32
	v_fmac_f32_e32 v86, v26, v12
	v_fma_f32 v14, v50, v14, v32
	v_fmac_f32_e32 v86, v27, v13
	v_fma_f32 v15, v51, v15, v32
	v_fmac_f32_e32 v86, v28, v14
	v_fma_f32 v16, v52, v16, v32
	v_fmac_f32_e32 v86, v29, v15
	v_fma_f32 v17, v53, v17, v32
	v_fmac_f32_e32 v86, v30, v16
	v_fmac_f32_e32 v86, v31, v17
	ds_write_b32 v96, v86 offset:13824
	s_waitcnt lgkmcnt(3)
	ds_read_b128 v[24:27], v0 offset:1536
	ds_read_b128 v[28:31], v0 offset:1552
	ds_read_b128 v[46:49], v0 offset:6144
	ds_read_b128 v[50:53], v0 offset:6160
	ds_read_b32 v32, v1 offset:2240
	v_sub_f32_e32 v10, v10, v34
	v_sub_f32_e32 v11, v11, v34
	v_sub_f32_e32 v12, v12, v34
	v_sub_f32_e32 v13, v13, v34
	v_sub_f32_e32 v14, v14, v34
	v_sub_f32_e32 v15, v15, v34
	v_sub_f32_e32 v16, v16, v34
	v_sub_f32_e32 v17, v17, v34
	v_fma_f32 v10, v54, v10, v34
	v_fma_f32 v11, v55, v11, v34
	v_mul_f32_e32 v87, v38, v10
	v_fma_f32 v12, v56, v12, v34
	v_fmac_f32_e32 v87, v39, v11
	v_fma_f32 v13, v57, v13, v34
	v_fmac_f32_e32 v87, v40, v12
	v_fma_f32 v14, v58, v14, v34
	v_fmac_f32_e32 v87, v41, v13
	v_fma_f32 v15, v59, v15, v34
	v_fmac_f32_e32 v87, v42, v14
	v_fma_f32 v16, v60, v16, v34
	v_fmac_f32_e32 v87, v43, v15
	v_fma_f32 v17, v61, v17, v34
	v_fmac_f32_e32 v87, v44, v16
	v_fmac_f32_e32 v87, v45, v17
	ds_write_b32 v96, v87 offset:14080
	s_waitcnt lgkmcnt(1)
	ds_read_b128 v[38:41], v0 offset:1792
	ds_read_b128 v[42:45], v0 offset:1808
	ds_read_b128 v[54:57], v0 offset:6400
	ds_read_b128 v[58:61], v0 offset:6416
	ds_read_b32 v34, v1 offset:2272
	v_sub_f32_e32 v10, v10, v32
	v_sub_f32_e32 v11, v11, v32
	v_sub_f32_e32 v12, v12, v32
	s_waitcnt lgkmcnt(12)
	v_sub_f32_e32 v13, v13, v32
	v_sub_f32_e32 v14, v14, v32
	v_sub_f32_e32 v15, v15, v32
	v_add_f32_e32 v100, v100, v104
	v_sub_f32_e32 v16, v16, v32
	v_sub_f32_e32 v17, v17, v32
	v_fma_f32 v10, v46, v10, v32
	v_add_f32_e32 v101, v101, v105
	v_fma_f32 v11, v47, v11, v32
	v_mul_f32_e32 v86, v24, v10
	v_fma_f32 v12, v48, v12, v32
	v_add_f32_e32 v102, v102, v106
	v_fmac_f32_e32 v86, v25, v11
	v_fma_f32 v13, v49, v13, v32
	v_fmac_f32_e32 v86, v26, v12
	v_add_f32_e32 v103, v103, v107
	v_fma_f32 v14, v50, v14, v32
	v_fmac_f32_e32 v86, v27, v13
	v_fma_f32 v15, v51, v15, v32
	v_add_f32_e32 v100, v100, v101
	v_fmac_f32_e32 v86, v28, v14
	v_fma_f32 v16, v52, v16, v32
	v_fmac_f32_e32 v86, v29, v15
	v_add_f32_e32 v102, v102, v103
	v_fma_f32 v17, v53, v17, v32
	v_fmac_f32_e32 v86, v30, v16
	v_fmac_f32_e32 v86, v31, v17
	v_add_f32_e32 v100, v100, v102
	ds_write_b32 v96, v86 offset:14336
	v_cvt_pk_bf16_f32 v22, v100, v100
	ds_write_b16 v90, v22 offset:17792
	v_add_u32_e32 v90, 0x200, v90
	s_and_b32 s24, s12, 7
	s_cmp_eq_u32 s24, 0
	s_cbranch_scc0 .Lls2_8_noflush
	s_cmp_eq_u32 s12, 64
	s_cbranch_scc1 .Lls2_8_noflush
	s_waitcnt lgkmcnt(0)
	ds_read_b128 v[92:95], v91 offset:17408
	s_waitcnt lgkmcnt(0)
	global_store_dwordx4 v7, v[92:95], s[94:95]
	v_add_u32_e32 v7, 0x20000, v7
	s_nop 0
	ds_read_b128 v[92:95], v91 offset:18432
	s_waitcnt lgkmcnt(0)
	global_store_dwordx4 v7, v[92:95], s[94:95]
	v_add_u32_e32 v7, 0x20000, v7
	s_nop 0
	ds_read_b128 v[92:95], v91 offset:19456
	s_waitcnt lgkmcnt(0)
	global_store_dwordx4 v7, v[92:95], s[94:95]
	v_add_u32_e32 v7, 0x20000, v7
	s_nop 0
	ds_read_b128 v[92:95], v91 offset:20480
	s_waitcnt lgkmcnt(0)
	global_store_dwordx4 v7, v[92:95], s[94:95]
	v_add_u32_e32 v7, 0x20000, v7
	s_nop 0
	v_subrev_u32_e32 v90, 0x1000, v90
.Lls2_8_noflush:
	s_waitcnt lgkmcnt(2)
	ds_read_b128 v[24:27], v0 offset:2304
	ds_read_b128 v[28:31], v0 offset:2320
	s_waitcnt vmcnt(8)
	ds_read_b128 v[46:49], v0 offset:6656
	ds_read_b128 v[50:53], v0 offset:6672
	ds_read_b32 v32, v1 offset:4352
	v_sub_f32_e32 v10, v10, v34
	v_sub_f32_e32 v11, v11, v34
	v_sub_f32_e32 v12, v12, v34
	v_sub_f32_e32 v13, v13, v34
	v_sub_f32_e32 v14, v14, v34
	v_sub_f32_e32 v15, v15, v34
	v_sub_f32_e32 v16, v16, v34
	v_sub_f32_e32 v17, v17, v34
	v_fma_f32 v10, v54, v10, v34
	v_fma_f32 v11, v55, v11, v34
	v_mul_f32_e32 v87, v38, v10
	v_fma_f32 v12, v56, v12, v34
	v_fmac_f32_e32 v87, v39, v11
	v_fma_f32 v13, v57, v13, v34
	v_fmac_f32_e32 v87, v40, v12
	v_fma_f32 v14, v58, v14, v34
	v_fmac_f32_e32 v87, v41, v13
	v_fma_f32 v15, v59, v15, v34
	v_fmac_f32_e32 v87, v42, v14
	v_fma_f32 v16, v60, v16, v34
	v_fmac_f32_e32 v87, v43, v15
	v_fma_f32 v17, v61, v17, v34
	v_fmac_f32_e32 v87, v44, v16
	v_fmac_f32_e32 v87, v45, v17
	ds_write_b32 v96, v87 offset:14592
	s_waitcnt lgkmcnt(1)
	ds_read_b128 v[38:41], v0 offset:2560
	ds_read_b128 v[42:45], v0 offset:2576
	ds_read_b128 v[54:57], v0 offset:6912
	ds_read_b128 v[58:61], v0 offset:6928
	ds_read_b32 v34, v1 offset:4384
	v_sub_f32_e32 v10, v10, v32
	v_sub_f32_e32 v11, v11, v32
	v_sub_f32_e32 v12, v12, v32
	s_waitcnt vmcnt(15)
	v_sub_f32_e32 v13, v13, v32
	v_sub_f32_e32 v14, v14, v32
	v_sub_f32_e32 v15, v15, v32
	v_lshlrev_b32_e32 v78, 16, v70
	v_sub_f32_e32 v16, v16, v32
	v_sub_f32_e32 v17, v17, v32
	v_fma_f32 v10, v46, v10, v32
	v_and_b32_e32 v79, 0xffff0000, v70
	v_fma_f32 v11, v47, v11, v32
	v_mul_f32_e32 v86, v24, v10
	v_fma_f32 v12, v48, v12, v32
	v_lshlrev_b32_e32 v80, 16, v71
	v_fmac_f32_e32 v86, v25, v11
	v_fma_f32 v13, v49, v13, v32
	v_fmac_f32_e32 v86, v26, v12
	v_fma_f32 v14, v50, v14, v32
	v_fmac_f32_e32 v86, v27, v13
	v_fma_f32 v15, v51, v15, v32
	v_fmac_f32_e32 v86, v28, v14
	v_fma_f32 v16, v52, v16, v32
	v_fmac_f32_e32 v86, v29, v15
	v_fma_f32 v17, v53, v17, v32
	v_fmac_f32_e32 v86, v30, v16
	v_fmac_f32_e32 v86, v31, v17
	ds_write_b32 v96, v86 offset:14848
	s_waitcnt lgkmcnt(1)
	ds_read_b128 v[24:27], v0 offset:2816
	ds_read_b128 v[28:31], v0 offset:2832
	ds_read_b128 v[46:49], v0 offset:7168
	ds_read_b128 v[50:53], v0 offset:7184
	ds_read_b32 v32, v1 offset:4416
	v_sub_f32_e32 v10, v10, v34
	v_sub_f32_e32 v11, v11, v34
	v_sub_f32_e32 v12, v12, v34
	v_and_b32_e32 v81, 0xffff0000, v71
	v_sub_f32_e32 v13, v13, v34
	v_sub_f32_e32 v14, v14, v34
	v_sub_f32_e32 v15, v15, v34
	ds_write_b128 v2, v[78:81] offset:0
	v_sub_f32_e32 v16, v16, v34
	v_sub_f32_e32 v17, v17, v34
	v_fma_f32 v10, v54, v10, v34
	v_lshlrev_b32_e32 v82, 16, v72
	v_fma_f32 v11, v55, v11, v34
	v_mul_f32_e32 v87, v38, v10
	v_fma_f32 v12, v56, v12, v34
	v_and_b32_e32 v83, 0xffff0000, v72
	v_fmac_f32_e32 v87, v39, v11
	v_fma_f32 v13, v57, v13, v34
	v_fmac_f32_e32 v87, v40, v12
	v_fma_f32 v14, v58, v14, v34
	v_fmac_f32_e32 v87, v41, v13
	v_fma_f32 v15, v59, v15, v34
	v_fmac_f32_e32 v87, v42, v14
	v_fma_f32 v16, v60, v16, v34
	v_fmac_f32_e32 v87, v43, v15
	v_fma_f32 v17, v61, v17, v34
	v_fmac_f32_e32 v87, v44, v16
	v_fmac_f32_e32 v87, v45, v17
	ds_write_b32 v96, v87 offset:15104
	s_waitcnt lgkmcnt(2)
	ds_read_b128 v[38:41], v0 offset:3072
	ds_read_b128 v[42:45], v0 offset:3088
	ds_read_b128 v[54:57], v0 offset:7424
	ds_read_b128 v[58:61], v0 offset:7440
	ds_read_b32 v34, v1 offset:4448
	v_sub_f32_e32 v10, v10, v32
	v_sub_f32_e32 v11, v11, v32
	v_sub_f32_e32 v12, v12, v32
	v_lshlrev_b32_e32 v84, 16, v73
	v_sub_f32_e32 v13, v13, v32
	v_sub_f32_e32 v14, v14, v32
	v_sub_f32_e32 v15, v15, v32
	v_and_b32_e32 v85, 0xffff0000, v73
	v_sub_f32_e32 v16, v16, v32
	v_sub_f32_e32 v17, v17, v32
	v_fma_f32 v10, v46, v10, v32
	ds_write_b128 v2, v[82:85] offset:16
	v_fma_f32 v11, v47, v11, v32
	v_mul_f32_e32 v86, v24, v10
	v_fma_f32 v12, v48, v12, v32
	s_waitcnt vmcnt(14)
	v_fmac_f32_e32 v86, v25, v11
	v_fma_f32 v13, v49, v13, v32
	v_fmac_f32_e32 v86, v26, v12
	v_fma_f32 v14, v50, v14, v32
	v_fmac_f32_e32 v86, v27, v13
	v_fma_f32 v15, v51, v15, v32
	v_fmac_f32_e32 v86, v28, v14
	v_fma_f32 v16, v52, v16, v32
	v_fmac_f32_e32 v86, v29, v15
	v_fma_f32 v17, v53, v17, v32
	v_fmac_f32_e32 v86, v30, v16
	v_fmac_f32_e32 v86, v31, v17
	ds_write_b32 v96, v86 offset:15360
	s_waitcnt lgkmcnt(2)
	ds_read_b128 v[24:27], v0 offset:3328
	ds_read_b128 v[28:31], v0 offset:3344
	ds_read_b128 v[46:49], v0 offset:7680
	ds_read_b128 v[50:53], v0 offset:7696
	ds_read_b32 v32, v1 offset:4480
	v_sub_f32_e32 v10, v10, v34
	v_sub_f32_e32 v11, v11, v34
	v_sub_f32_e32 v12, v12, v34
	v_lshlrev_b32_e32 v35, 16, v35
	v_sub_f32_e32 v13, v13, v34
	v_sub_f32_e32 v14, v14, v34
	v_sub_f32_e32 v15, v15, v34
	s_nop 0
	v_sub_f32_e32 v16, v16, v34
	v_sub_f32_e32 v17, v17, v34
	v_fma_f32 v10, v54, v10, v34
	ds_write_b32 v4, v35 offset:2048
	v_fma_f32 v11, v55, v11, v34
	v_mul_f32_e32 v87, v38, v10
	v_fma_f32 v12, v56, v12, v34
	v_fmac_f32_e32 v87, v39, v11
	v_fma_f32 v13, v57, v13, v34
	v_fmac_f32_e32 v87, v40, v12
	v_fma_f32 v14, v58, v14, v34
	v_fmac_f32_e32 v87, v41, v13
	v_fma_f32 v15, v59, v15, v34
	v_fmac_f32_e32 v87, v42, v14
	v_fma_f32 v16, v60, v16, v34
	v_fmac_f32_e32 v87, v43, v15
	v_fma_f32 v17, v61, v17, v34
	v_fmac_f32_e32 v87, v44, v16
	v_fmac_f32_e32 v87, v45, v17
	ds_write_b32 v96, v87 offset:15616
	s_waitcnt lgkmcnt(2)
	ds_read_b128 v[38:41], v0 offset:3584
	ds_read_b128 v[42:45], v0 offset:3600
	ds_read_b128 v[54:57], v0 offset:7936
	ds_read_b128 v[58:61], v0 offset:7952
	ds_read_b32 v34, v1 offset:4512
	v_sub_f32_e32 v10, v10, v32
	v_sub_f32_e32 v11, v11, v32
	v_sub_f32_e32 v12, v12, v32
	global_load_dwordx4 v[70:73], v5, s[94:95]
	global_load_ushort v35, v6, s[94:95]
	v_add_u32_e32 v5, 0x6800, v5
	v_add_u32_e32 v6, 0x10000, v6
	v_sub_f32_e32 v13, v13, v32
	v_sub_f32_e32 v14, v14, v32
	v_sub_f32_e32 v15, v15, v32
	s_add_i32 m0, s29, 0x1200
	s_nop 0
	global_load_lds_dwordx4 v8, s[94:95]
	s_add_i32 m0, s29, 0x1600
	v_add_u32_e32 v8, 0x3180, v8
	global_load_lds_dwordx4 v88, s[94:95]
	v_add_u32_e32 v88, 0x3180, v88
	v_sub_f32_e32 v16, v16, v32
	v_sub_f32_e32 v17, v17, v32
	v_fma_f32 v10, v46, v10, v32
	ds_read_b128 v[100:103], v97 offset:12800
	v_fma_f32 v11, v47, v11, v32
	v_mul_f32_e32 v86, v24, v10
	v_fma_f32 v12, v48, v12, v32
	ds_read_b128 v[104:107], v98 offset:12800
	v_fmac_f32_e32 v86, v25, v11
	v_fma_f32 v13, v49, v13, v32
	v_fmac_f32_e32 v86, v26, v12
	v_fma_f32 v14, v50, v14, v32
	v_fmac_f32_e32 v86, v27, v13
	v_fma_f32 v15, v51, v15, v32
	v_fmac_f32_e32 v86, v28, v14
	v_fma_f32 v16, v52, v16, v32
	v_fmac_f32_e32 v86, v29, v15
	v_fma_f32 v17, v53, v17, v32
	v_fmac_f32_e32 v86, v30, v16
	v_fmac_f32_e32 v86, v31, v17
	ds_write_b32 v96, v86 offset:15872
	s_waitcnt lgkmcnt(3)
	ds_read_b128 v[24:27], v0 offset:3840
	ds_read_b128 v[28:31], v0 offset:3856
	ds_read_b128 v[46:49], v0 offset:8192
	ds_read_b128 v[50:53], v0 offset:8208
	ds_read_b32 v32, v1 offset:4544
	v_sub_f32_e32 v10, v10, v34
	v_sub_f32_e32 v11, v11, v34
	v_sub_f32_e32 v12, v12, v34
	v_sub_f32_e32 v13, v13, v34
	v_sub_f32_e32 v14, v14, v34
	v_sub_f32_e32 v15, v15, v34
	v_sub_f32_e32 v16, v16, v34
	v_sub_f32_e32 v17, v17, v34
	v_fma_f32 v10, v54, v10, v34
	v_fma_f32 v11, v55, v11, v34
	v_mul_f32_e32 v87, v38, v10
	v_fma_f32 v12, v56, v12, v34
	v_fmac_f32_e32 v87, v39, v11
	v_fma_f32 v13, v57, v13, v34
	v_fmac_f32_e32 v87, v40, v12
	v_fma_f32 v14, v58, v14, v34
	v_fmac_f32_e32 v87, v41, v13
	v_fma_f32 v15, v59, v15, v34
	v_fmac_f32_e32 v87, v42, v14
	v_fma_f32 v16, v60, v16, v34
	v_fmac_f32_e32 v87, v43, v15
	v_fma_f32 v17, v61, v17, v34
	v_fmac_f32_e32 v87, v44, v16
	v_fmac_f32_e32 v87, v45, v17
	ds_write_b32 v96, v87 offset:16128
	s_waitcnt lgkmcnt(1)
	ds_read_b128 v[38:41], v0 offset:4096
	ds_read_b128 v[42:45], v0 offset:4112
	ds_read_b128 v[54:57], v0 offset:8448
	ds_read_b128 v[58:61], v0 offset:8464
	ds_read_b32 v34, v1 offset:4576
	v_sub_f32_e32 v10, v10, v32
	v_sub_f32_e32 v11, v11, v32
	v_sub_f32_e32 v12, v12, v32
	s_waitcnt lgkmcnt(12)
	v_sub_f32_e32 v13, v13, v32
	v_sub_f32_e32 v14, v14, v32
	v_sub_f32_e32 v15, v15, v32
	v_add_f32_e32 v100, v100, v104
	v_sub_f32_e32 v16, v16, v32
	v_sub_f32_e32 v17, v17, v32
	v_fma_f32 v10, v46, v10, v32
	v_add_f32_e32 v101, v101, v105
	v_fma_f32 v11, v47, v11, v32
	v_mul_f32_e32 v86, v24, v10
	v_fma_f32 v12, v48, v12, v32
	v_add_f32_e32 v102, v102, v106
	v_fmac_f32_e32 v86, v25, v11
	v_fma_f32 v13, v49, v13, v32
	v_fmac_f32_e32 v86, v26, v12
	v_add_f32_e32 v103, v103, v107
	v_fma_f32 v14, v50, v14, v32
	v_fmac_f32_e32 v86, v27, v13
	v_fma_f32 v15, v51, v15, v32
	v_add_f32_e32 v100, v100, v101
	v_fmac_f32_e32 v86, v28, v14
	v_fma_f32 v16, v52, v16, v32
	v_fmac_f32_e32 v86, v29, v15
	v_add_f32_e32 v102, v102, v103
	v_fma_f32 v17, v53, v17, v32
	v_fmac_f32_e32 v86, v30, v16
	v_fmac_f32_e32 v86, v31, v17
	v_add_f32_e32 v100, v100, v102
	ds_write_b32 v96, v86 offset:16384
	v_cvt_pk_bf16_f32 v22, v100, v100
	ds_write_b16 v90, v22 offset:17408
	s_waitcnt lgkmcnt(2)
	ds_read_b128 v[24:27], v0 offset:0
	ds_read_b128 v[28:31], v0 offset:16
	s_waitcnt vmcnt(8)
	ds_read_b128 v[46:49], v0 offset:8704
	ds_read_b128 v[50:53], v0 offset:8720
	ds_read_b32 v32, v1 offset:2048
	v_sub_f32_e32 v10, v10, v34
	v_sub_f32_e32 v11, v11, v34
	v_sub_f32_e32 v12, v12, v34
	v_sub_f32_e32 v13, v13, v34
	v_sub_f32_e32 v14, v14, v34
	v_sub_f32_e32 v15, v15, v34
	v_sub_f32_e32 v16, v16, v34
	v_sub_f32_e32 v17, v17, v34
	v_fma_f32 v10, v54, v10, v34
	v_fma_f32 v11, v55, v11, v34
	v_mul_f32_e32 v87, v38, v10
	v_fma_f32 v12, v56, v12, v34
	v_fmac_f32_e32 v87, v39, v11
	v_fma_f32 v13, v57, v13, v34
	v_fmac_f32_e32 v87, v40, v12
	v_fma_f32 v14, v58, v14, v34
	v_fmac_f32_e32 v87, v41, v13
	v_fma_f32 v15, v59, v15, v34
	v_fmac_f32_e32 v87, v42, v14
	v_fma_f32 v16, v60, v16, v34
	v_fmac_f32_e32 v87, v43, v15
	v_fma_f32 v17, v61, v17, v34
	v_fmac_f32_e32 v87, v44, v16
	v_fmac_f32_e32 v87, v45, v17
	ds_write_b32 v96, v87 offset:16640
	s_waitcnt lgkmcnt(1)
	ds_read_b128 v[38:41], v0 offset:256
	ds_read_b128 v[42:45], v0 offset:272
	ds_read_b128 v[54:57], v0 offset:8960
	ds_read_b128 v[58:61], v0 offset:8976
	ds_read_b32 v34, v1 offset:2080
	v_sub_f32_e32 v10, v10, v32
	v_sub_f32_e32 v11, v11, v32
	v_sub_f32_e32 v12, v12, v32
	s_waitcnt vmcnt(15)
	v_sub_f32_e32 v13, v13, v32
	v_sub_f32_e32 v14, v14, v32
	v_sub_f32_e32 v15, v15, v32
	v_lshlrev_b32_e32 v78, 16, v74
	v_sub_f32_e32 v16, v16, v32
	v_sub_f32_e32 v17, v17, v32
	v_fma_f32 v10, v46, v10, v32
	v_and_b32_e32 v79, 0xffff0000, v74
	v_fma_f32 v11, v47, v11, v32
	v_mul_f32_e32 v86, v24, v10
	v_fma_f32 v12, v48, v12, v32
	v_lshlrev_b32_e32 v80, 16, v75
	v_fmac_f32_e32 v86, v25, v11
	v_fma_f32 v13, v49, v13, v32
	v_fmac_f32_e32 v86, v26, v12
	v_fma_f32 v14, v50, v14, v32
	v_fmac_f32_e32 v86, v27, v13
	v_fma_f32 v15, v51, v15, v32
	v_fmac_f32_e32 v86, v28, v14
	v_fma_f32 v16, v52, v16, v32
	v_fmac_f32_e32 v86, v29, v15
	v_fma_f32 v17, v53, v17, v32
	v_fmac_f32_e32 v86, v30, v16
	v_fmac_f32_e32 v86, v31, v17
	ds_write_b32 v96, v86 offset:12800
	s_waitcnt lgkmcnt(1)
	ds_read_b128 v[24:27], v0 offset:512
	ds_read_b128 v[28:31], v0 offset:528
	ds_read_b128 v[46:49], v0 offset:9216
	ds_read_b128 v[50:53], v0 offset:9232
	ds_read_b32 v32, v1 offset:2112
	v_sub_f32_e32 v10, v10, v34
	v_sub_f32_e32 v11, v11, v34
	v_sub_f32_e32 v12, v12, v34
	v_and_b32_e32 v81, 0xffff0000, v75
	v_sub_f32_e32 v13, v13, v34
	v_sub_f32_e32 v14, v14, v34
	v_sub_f32_e32 v15, v15, v34
	ds_write_b128 v2, v[78:81] offset:2304
	v_sub_f32_e32 v16, v16, v34
	v_sub_f32_e32 v17, v17, v34
	v_fma_f32 v10, v54, v10, v34
	v_lshlrev_b32_e32 v82, 16, v76
	v_fma_f32 v11, v55, v11, v34
	v_mul_f32_e32 v87, v38, v10
	v_fma_f32 v12, v56, v12, v34
	v_and_b32_e32 v83, 0xffff0000, v76
	v_fmac_f32_e32 v87, v39, v11
	v_fma_f32 v13, v57, v13, v34
	v_fmac_f32_e32 v87, v40, v12
	v_fma_f32 v14, v58, v14, v34
	v_fmac_f32_e32 v87, v41, v13
	v_fma_f32 v15, v59, v15, v34
	v_fmac_f32_e32 v87, v42, v14
	v_fma_f32 v16, v60, v16, v34
	v_fmac_f32_e32 v87, v43, v15
	v_fma_f32 v17, v61, v17, v34
	v_fmac_f32_e32 v87, v44, v16
	v_fmac_f32_e32 v87, v45, v17
	ds_write_b32 v96, v87 offset:13056
	s_waitcnt lgkmcnt(2)
	ds_read_b128 v[38:41], v0 offset:768
	ds_read_b128 v[42:45], v0 offset:784
	ds_read_b128 v[54:57], v0 offset:9472
	ds_read_b128 v[58:61], v0 offset:9488
	ds_read_b32 v34, v1 offset:2144
	v_sub_f32_e32 v10, v10, v32
	v_sub_f32_e32 v11, v11, v32
	v_sub_f32_e32 v12, v12, v32
	v_lshlrev_b32_e32 v84, 16, v77
	v_sub_f32_e32 v13, v13, v32
	v_sub_f32_e32 v14, v14, v32
	v_sub_f32_e32 v15, v15, v32
	v_and_b32_e32 v85, 0xffff0000, v77
	v_sub_f32_e32 v16, v16, v32
	v_sub_f32_e32 v17, v17, v32
	v_fma_f32 v10, v46, v10, v32
	ds_write_b128 v2, v[82:85] offset:2320
	v_fma_f32 v11, v47, v11, v32
	v_mul_f32_e32 v86, v24, v10
	v_fma_f32 v12, v48, v12, v32
	s_waitcnt vmcnt(14)
	v_fmac_f32_e32 v86, v25, v11
	v_fma_f32 v13, v49, v13, v32
	v_fmac_f32_e32 v86, v26, v12
	v_fma_f32 v14, v50, v14, v32
	v_fmac_f32_e32 v86, v27, v13
	v_fma_f32 v15, v51, v15, v32
	v_fmac_f32_e32 v86, v28, v14
	v_fma_f32 v16, v52, v16, v32
	v_fmac_f32_e32 v86, v29, v15
	v_fma_f32 v17, v53, v17, v32
	v_fmac_f32_e32 v86, v30, v16
	v_fmac_f32_e32 v86, v31, v17
	ds_write_b32 v96, v86 offset:13312
	s_waitcnt lgkmcnt(2)
	ds_read_b128 v[24:27], v0 offset:1024
	ds_read_b128 v[28:31], v0 offset:1040
	ds_read_b128 v[46:49], v0 offset:9728
	ds_read_b128 v[50:53], v0 offset:9744
	ds_read_b32 v32, v1 offset:2176
	v_sub_f32_e32 v10, v10, v34
	v_sub_f32_e32 v11, v11, v34
	v_sub_f32_e32 v12, v12, v34
	v_lshlrev_b32_e32 v36, 16, v36
	v_sub_f32_e32 v13, v13, v34
	v_sub_f32_e32 v14, v14, v34
	v_sub_f32_e32 v15, v15, v34
	s_nop 0
	v_sub_f32_e32 v16, v16, v34
	v_sub_f32_e32 v17, v17, v34
	v_fma_f32 v10, v54, v10, v34
	ds_write_b32 v4, v36 offset:4352
	v_fma_f32 v11, v55, v11, v34
	v_mul_f32_e32 v87, v38, v10
	v_fma_f32 v12, v56, v12, v34
	v_fmac_f32_e32 v87, v39, v11
	v_fma_f32 v13, v57, v13, v34
	v_fmac_f32_e32 v87, v40, v12
	v_fma_f32 v14, v58, v14, v34
	v_fmac_f32_e32 v87, v41, v13
	v_fma_f32 v15, v59, v15, v34
	v_fmac_f32_e32 v87, v42, v14
	v_fma_f32 v16, v60, v16, v34
	v_fmac_f32_e32 v87, v43, v15
	v_fma_f32 v17, v61, v17, v34
	v_fmac_f32_e32 v87, v44, v16
	v_fmac_f32_e32 v87, v45, v17
	ds_write_b32 v96, v87 offset:13568
	s_waitcnt lgkmcnt(2)
	ds_read_b128 v[38:41], v0 offset:1280
	ds_read_b128 v[42:45], v0 offset:1296
	ds_read_b128 v[54:57], v0 offset:9984
	ds_read_b128 v[58:61], v0 offset:10000
	ds_read_b32 v34, v1 offset:2208
	v_sub_f32_e32 v10, v10, v32
	v_sub_f32_e32 v11, v11, v32
	v_sub_f32_e32 v12, v12, v32
	global_load_dwordx4 v[74:77], v5, s[94:95]
	global_load_ushort v36, v6, s[94:95]
	v_add_u32_e32 v5, 0x6800, v5
	v_add_u32_e32 v6, 0x10000, v6
	v_sub_f32_e32 v13, v13, v32
	v_sub_f32_e32 v14, v14, v32
	v_sub_f32_e32 v15, v15, v32
	s_add_i32 m0, s29, 0x1a00
	s_nop 0
	global_load_lds_dwordx4 v8, s[94:95]
	s_add_i32 m0, s29, 0x1e00
	v_add_u32_e32 v8, 0x3180, v8
	global_load_lds_dwordx4 v88, s[94:95]
	v_add_u32_e32 v88, 0x3180, v88
	v_sub_f32_e32 v16, v16, v32
	v_sub_f32_e32 v17, v17, v32
	v_fma_f32 v10, v46, v10, v32
	ds_read_b128 v[100:103], v97 offset:14848
	v_fma_f32 v11, v47, v11, v32
	v_mul_f32_e32 v86, v24, v10
	v_fma_f32 v12, v48, v12, v32
	ds_read_b128 v[104:107], v98 offset:14848
	v_fmac_f32_e32 v86, v25, v11
	v_fma_f32 v13, v49, v13, v32
	v_fmac_f32_e32 v86, v26, v12
	v_fma_f32 v14, v50, v14, v32
	v_fmac_f32_e32 v86, v27, v13
	v_fma_f32 v15, v51, v15, v32
	v_fmac_f32_e32 v86, v28, v14
	v_fma_f32 v16, v52, v16, v32
	v_fmac_f32_e32 v86, v29, v15
	v_fma_f32 v17, v53, v17, v32
	v_fmac_f32_e32 v86, v30, v16
	v_fmac_f32_e32 v86, v31, v17
	ds_write_b32 v96, v86 offset:13824
	s_waitcnt lgkmcnt(3)
	ds_read_b128 v[24:27], v0 offset:1536
	ds_read_b128 v[28:31], v0 offset:1552
	ds_read_b128 v[46:49], v0 offset:10240
	ds_read_b128 v[50:53], v0 offset:10256
	ds_read_b32 v32, v1 offset:2240
	v_sub_f32_e32 v10, v10, v34
	v_sub_f32_e32 v11, v11, v34
	v_sub_f32_e32 v12, v12, v34
	v_sub_f32_e32 v13, v13, v34
	v_sub_f32_e32 v14, v14, v34
	v_sub_f32_e32 v15, v15, v34
	v_sub_f32_e32 v16, v16, v34
	v_sub_f32_e32 v17, v17, v34
	v_fma_f32 v10, v54, v10, v34
	v_fma_f32 v11, v55, v11, v34
	v_mul_f32_e32 v87, v38, v10
	v_fma_f32 v12, v56, v12, v34
	v_fmac_f32_e32 v87, v39, v11
	v_fma_f32 v13, v57, v13, v34
	v_fmac_f32_e32 v87, v40, v12
	v_fma_f32 v14, v58, v14, v34
	v_fmac_f32_e32 v87, v41, v13
	v_fma_f32 v15, v59, v15, v34
	v_fmac_f32_e32 v87, v42, v14
	v_fma_f32 v16, v60, v16, v34
	v_fmac_f32_e32 v87, v43, v15
	v_fma_f32 v17, v61, v17, v34
	v_fmac_f32_e32 v87, v44, v16
	v_fmac_f32_e32 v87, v45, v17
	ds_write_b32 v96, v87 offset:14080
	s_waitcnt lgkmcnt(1)
	ds_read_b128 v[38:41], v0 offset:1792
	ds_read_b128 v[42:45], v0 offset:1808
	ds_read_b128 v[54:57], v0 offset:10496
	ds_read_b128 v[58:61], v0 offset:10512
	ds_read_b32 v34, v1 offset:2272
	v_sub_f32_e32 v10, v10, v32
	v_sub_f32_e32 v11, v11, v32
	v_sub_f32_e32 v12, v12, v32
	s_waitcnt lgkmcnt(12)
	v_sub_f32_e32 v13, v13, v32
	v_sub_f32_e32 v14, v14, v32
	v_sub_f32_e32 v15, v15, v32
	v_add_f32_e32 v100, v100, v104
	v_sub_f32_e32 v16, v16, v32
	v_sub_f32_e32 v17, v17, v32
	v_fma_f32 v10, v46, v10, v32
	v_add_f32_e32 v101, v101, v105
	v_fma_f32 v11, v47, v11, v32
	v_mul_f32_e32 v86, v24, v10
	v_fma_f32 v12, v48, v12, v32
	v_add_f32_e32 v102, v102, v106
	v_fmac_f32_e32 v86, v25, v11
	v_fma_f32 v13, v49, v13, v32
	v_fmac_f32_e32 v86, v26, v12
	v_add_f32_e32 v103, v103, v107
	v_fma_f32 v14, v50, v14, v32
	v_fmac_f32_e32 v86, v27, v13
	v_fma_f32 v15, v51, v15, v32
	v_add_f32_e32 v100, v100, v101
	v_fmac_f32_e32 v86, v28, v14
	v_fma_f32 v16, v52, v16, v32
	v_fmac_f32_e32 v86, v29, v15
	v_add_f32_e32 v102, v102, v103
	v_fma_f32 v17, v53, v17, v32
	v_fmac_f32_e32 v86, v30, v16
	v_fmac_f32_e32 v86, v31, v17
	v_add_f32_e32 v100, v100, v102
	ds_write_b32 v96, v86 offset:14336
	v_cvt_pk_bf16_f32 v22, v100, v100
	ds_write_b16 v90, v22 offset:17536
	s_waitcnt lgkmcnt(2)
	ds_read_b128 v[24:27], v0 offset:2304
	ds_read_b128 v[28:31], v0 offset:2320
	s_waitcnt vmcnt(8)
	ds_read_b128 v[46:49], v0 offset:10752
	ds_read_b128 v[50:53], v0 offset:10768
	ds_read_b32 v32, v1 offset:4352
	v_sub_f32_e32 v10, v10, v34
	v_sub_f32_e32 v11, v11, v34
	v_sub_f32_e32 v12, v12, v34
	v_sub_f32_e32 v13, v13, v34
	v_sub_f32_e32 v14, v14, v34
	v_sub_f32_e32 v15, v15, v34
	v_sub_f32_e32 v16, v16, v34
	v_sub_f32_e32 v17, v17, v34
	v_fma_f32 v10, v54, v10, v34
	v_fma_f32 v11, v55, v11, v34
	v_mul_f32_e32 v87, v38, v10
	v_fma_f32 v12, v56, v12, v34
	v_fmac_f32_e32 v87, v39, v11
	v_fma_f32 v13, v57, v13, v34
	v_fmac_f32_e32 v87, v40, v12
	v_fma_f32 v14, v58, v14, v34
	v_fmac_f32_e32 v87, v41, v13
	v_fma_f32 v15, v59, v15, v34
	v_fmac_f32_e32 v87, v42, v14
	v_fma_f32 v16, v60, v16, v34
	v_fmac_f32_e32 v87, v43, v15
	v_fma_f32 v17, v61, v17, v34
	v_fmac_f32_e32 v87, v44, v16
	v_fmac_f32_e32 v87, v45, v17
	ds_write_b32 v96, v87 offset:14592
	s_waitcnt lgkmcnt(1)
	ds_read_b128 v[38:41], v0 offset:2560
	ds_read_b128 v[42:45], v0 offset:2576
	ds_read_b128 v[54:57], v0 offset:11008
	ds_read_b128 v[58:61], v0 offset:11024
	ds_read_b32 v34, v1 offset:4384
	v_sub_f32_e32 v10, v10, v32
	v_sub_f32_e32 v11, v11, v32
	v_sub_f32_e32 v12, v12, v32
	s_waitcnt vmcnt(15)
	v_sub_f32_e32 v13, v13, v32
	v_sub_f32_e32 v14, v14, v32
	v_sub_f32_e32 v15, v15, v32
	v_lshlrev_b32_e32 v78, 16, v62
	v_sub_f32_e32 v16, v16, v32
	v_sub_f32_e32 v17, v17, v32
	v_fma_f32 v10, v46, v10, v32
	v_and_b32_e32 v79, 0xffff0000, v62
	v_fma_f32 v11, v47, v11, v32
	v_mul_f32_e32 v86, v24, v10
	v_fma_f32 v12, v48, v12, v32
	v_lshlrev_b32_e32 v80, 16, v63
	v_fmac_f32_e32 v86, v25, v11
	v_fma_f32 v13, v49, v13, v32
	v_fmac_f32_e32 v86, v26, v12
	v_fma_f32 v14, v50, v14, v32
	v_fmac_f32_e32 v86, v27, v13
	v_fma_f32 v15, v51, v15, v32
	v_fmac_f32_e32 v86, v28, v14
	v_fma_f32 v16, v52, v16, v32
	v_fmac_f32_e32 v86, v29, v15
	v_fma_f32 v17, v53, v17, v32
	v_fmac_f32_e32 v86, v30, v16
	v_fmac_f32_e32 v86, v31, v17
	ds_write_b32 v96, v86 offset:14848
	s_waitcnt lgkmcnt(1)
	ds_read_b128 v[24:27], v0 offset:2816
	ds_read_b128 v[28:31], v0 offset:2832
	ds_read_b128 v[46:49], v0 offset:11264
	ds_read_b128 v[50:53], v0 offset:11280
	ds_read_b32 v32, v1 offset:4416
	v_sub_f32_e32 v10, v10, v34
	v_sub_f32_e32 v11, v11, v34
	v_sub_f32_e32 v12, v12, v34
	v_and_b32_e32 v81, 0xffff0000, v63
	v_sub_f32_e32 v13, v13, v34
	v_sub_f32_e32 v14, v14, v34
	v_sub_f32_e32 v15, v15, v34
	ds_write_b128 v2, v[78:81] offset:0
	v_sub_f32_e32 v16, v16, v34
	v_sub_f32_e32 v17, v17, v34
	v_fma_f32 v10, v54, v10, v34
	v_lshlrev_b32_e32 v82, 16, v64
	v_fma_f32 v11, v55, v11, v34
	v_mul_f32_e32 v87, v38, v10
	v_fma_f32 v12, v56, v12, v34
	v_and_b32_e32 v83, 0xffff0000, v64
	v_fmac_f32_e32 v87, v39, v11
	v_fma_f32 v13, v57, v13, v34
	v_fmac_f32_e32 v87, v40, v12
	v_fma_f32 v14, v58, v14, v34
	v_fmac_f32_e32 v87, v41, v13
	v_fma_f32 v15, v59, v15, v34
	v_fmac_f32_e32 v87, v42, v14
	v_fma_f32 v16, v60, v16, v34
	v_fmac_f32_e32 v87, v43, v15
	v_fma_f32 v17, v61, v17, v34
	v_fmac_f32_e32 v87, v44, v16
	v_fmac_f32_e32 v87, v45, v17
	ds_write_b32 v96, v87 offset:15104
	s_waitcnt lgkmcnt(2)
	ds_read_b128 v[38:41], v0 offset:3072
	ds_read_b128 v[42:45], v0 offset:3088
	ds_read_b128 v[54:57], v0 offset:11520
	ds_read_b128 v[58:61], v0 offset:11536
	ds_read_b32 v34, v1 offset:4448
	v_sub_f32_e32 v10, v10, v32
	v_sub_f32_e32 v11, v11, v32
	v_sub_f32_e32 v12, v12, v32
	v_lshlrev_b32_e32 v84, 16, v65
	v_sub_f32_e32 v13, v13, v32
	v_sub_f32_e32 v14, v14, v32
	v_sub_f32_e32 v15, v15, v32
	v_and_b32_e32 v85, 0xffff0000, v65
	v_sub_f32_e32 v16, v16, v32
	v_sub_f32_e32 v17, v17, v32
	v_fma_f32 v10, v46, v10, v32
	ds_write_b128 v2, v[82:85] offset:16
	v_fma_f32 v11, v47, v11, v32
	v_mul_f32_e32 v86, v24, v10
	v_fma_f32 v12, v48, v12, v32
	s_waitcnt vmcnt(14)
	v_fmac_f32_e32 v86, v25, v11
	v_fma_f32 v13, v49, v13, v32
	v_fmac_f32_e32 v86, v26, v12
	v_fma_f32 v14, v50, v14, v32
	v_fmac_f32_e32 v86, v27, v13
	v_fma_f32 v15, v51, v15, v32
	v_fmac_f32_e32 v86, v28, v14
	v_fma_f32 v16, v52, v16, v32
	v_fmac_f32_e32 v86, v29, v15
	v_fma_f32 v17, v53, v17, v32
	v_fmac_f32_e32 v86, v30, v16
	v_fmac_f32_e32 v86, v31, v17
	ds_write_b32 v96, v86 offset:15360
	s_waitcnt lgkmcnt(2)
	ds_read_b128 v[24:27], v0 offset:3328
	ds_read_b128 v[28:31], v0 offset:3344
	ds_read_b128 v[46:49], v0 offset:11776
	ds_read_b128 v[50:53], v0 offset:11792
	ds_read_b32 v32, v1 offset:4480
	v_sub_f32_e32 v10, v10, v34
	v_sub_f32_e32 v11, v11, v34
	v_sub_f32_e32 v12, v12, v34
	v_lshlrev_b32_e32 v23, 16, v23
	v_sub_f32_e32 v13, v13, v34
	v_sub_f32_e32 v14, v14, v34
	v_sub_f32_e32 v15, v15, v34
	s_nop 0
	v_sub_f32_e32 v16, v16, v34
	v_sub_f32_e32 v17, v17, v34
	v_fma_f32 v10, v54, v10, v34
	ds_write_b32 v4, v23 offset:2048
	v_fma_f32 v11, v55, v11, v34
	v_mul_f32_e32 v87, v38, v10
	v_fma_f32 v12, v56, v12, v34
	v_fmac_f32_e32 v87, v39, v11
	v_fma_f32 v13, v57, v13, v34
	v_fmac_f32_e32 v87, v40, v12
	v_fma_f32 v14, v58, v14, v34
	v_fmac_f32_e32 v87, v41, v13
	v_fma_f32 v15, v59, v15, v34
	v_fmac_f32_e32 v87, v42, v14
	v_fma_f32 v16, v60, v16, v34
	v_fmac_f32_e32 v87, v43, v15
	v_fma_f32 v17, v61, v17, v34
	v_fmac_f32_e32 v87, v44, v16
	v_fmac_f32_e32 v87, v45, v17
	ds_write_b32 v96, v87 offset:15616
	s_waitcnt lgkmcnt(2)
	ds_read_b128 v[38:41], v0 offset:3584
	ds_read_b128 v[42:45], v0 offset:3600
	ds_read_b128 v[54:57], v0 offset:12032
	ds_read_b128 v[58:61], v0 offset:12048
	ds_read_b32 v34, v1 offset:4512
	v_sub_f32_e32 v10, v10, v32
	v_sub_f32_e32 v11, v11, v32
	v_sub_f32_e32 v12, v12, v32
	global_load_dwordx4 v[62:65], v5, s[94:95]
	global_load_ushort v23, v6, s[94:95]
	v_add_u32_e32 v5, 0x6800, v5
	v_add_u32_e32 v6, 0x10000, v6
	v_sub_f32_e32 v13, v13, v32
	v_sub_f32_e32 v14, v14, v32
	v_sub_f32_e32 v15, v15, v32
	s_add_i32 m0, s29, 0x2200
	s_nop 0
	global_load_lds_dwordx4 v8, s[94:95]
	s_add_i32 m0, s29, 0x2600
	v_add_u32_e32 v8, 0x3180, v8
	global_load_lds_dwordx4 v88, s[94:95]
	v_add_u32_e32 v88, 0x3180, v88
	v_sub_f32_e32 v16, v16, v32
	v_sub_f32_e32 v17, v17, v32
	v_fma_f32 v10, v46, v10, v32
	ds_read_b128 v[100:103], v97 offset:12800
	v_fma_f32 v11, v47, v11, v32
	v_mul_f32_e32 v86, v24, v10
	v_fma_f32 v12, v48, v12, v32
	ds_read_b128 v[104:107], v98 offset:12800
	v_fmac_f32_e32 v86, v25, v11
	v_fma_f32 v13, v49, v13, v32
	v_fmac_f32_e32 v86, v26, v12
	v_fma_f32 v14, v50, v14, v32
	v_fmac_f32_e32 v86, v27, v13
	v_fma_f32 v15, v51, v15, v32
	v_fmac_f32_e32 v86, v28, v14
	v_fma_f32 v16, v52, v16, v32
	v_fmac_f32_e32 v86, v29, v15
	v_fma_f32 v17, v53, v17, v32
	v_fmac_f32_e32 v86, v30, v16
	v_fmac_f32_e32 v86, v31, v17
	ds_write_b32 v96, v86 offset:15872
	s_waitcnt lgkmcnt(3)
	ds_read_b128 v[24:27], v0 offset:3840
	ds_read_b128 v[28:31], v0 offset:3856
	ds_read_b128 v[46:49], v0 offset:12288
	ds_read_b128 v[50:53], v0 offset:12304
	ds_read_b32 v32, v1 offset:4544
	v_sub_f32_e32 v10, v10, v34
	v_sub_f32_e32 v11, v11, v34
	v_sub_f32_e32 v12, v12, v34
	v_sub_f32_e32 v13, v13, v34
	v_sub_f32_e32 v14, v14, v34
	v_sub_f32_e32 v15, v15, v34
	v_sub_f32_e32 v16, v16, v34
	v_sub_f32_e32 v17, v17, v34
	v_fma_f32 v10, v54, v10, v34
	v_fma_f32 v11, v55, v11, v34
	v_mul_f32_e32 v87, v38, v10
	v_fma_f32 v12, v56, v12, v34
	v_fmac_f32_e32 v87, v39, v11
	v_fma_f32 v13, v57, v13, v34
	v_fmac_f32_e32 v87, v40, v12
	v_fma_f32 v14, v58, v14, v34
	v_fmac_f32_e32 v87, v41, v13
	v_fma_f32 v15, v59, v15, v34
	v_fmac_f32_e32 v87, v42, v14
	v_fma_f32 v16, v60, v16, v34
	v_fmac_f32_e32 v87, v43, v15
	v_fma_f32 v17, v61, v17, v34
	v_fmac_f32_e32 v87, v44, v16
	v_fmac_f32_e32 v87, v45, v17
	ds_write_b32 v96, v87 offset:16128
	s_waitcnt lgkmcnt(1)
	ds_read_b128 v[38:41], v0 offset:4096
	ds_read_b128 v[42:45], v0 offset:4112
	ds_read_b128 v[54:57], v0 offset:12544
	ds_read_b128 v[58:61], v0 offset:12560
	ds_read_b32 v34, v1 offset:4576
	v_sub_f32_e32 v10, v10, v32
	v_sub_f32_e32 v11, v11, v32
	v_sub_f32_e32 v12, v12, v32
	s_waitcnt lgkmcnt(12)
	v_sub_f32_e32 v13, v13, v32
	v_sub_f32_e32 v14, v14, v32
	v_sub_f32_e32 v15, v15, v32
	v_add_f32_e32 v100, v100, v104
	v_sub_f32_e32 v16, v16, v32
	v_sub_f32_e32 v17, v17, v32
	v_fma_f32 v10, v46, v10, v32
	v_add_f32_e32 v101, v101, v105
	v_fma_f32 v11, v47, v11, v32
	v_mul_f32_e32 v86, v24, v10
	v_fma_f32 v12, v48, v12, v32
	v_add_f32_e32 v102, v102, v106
	v_fmac_f32_e32 v86, v25, v11
	v_fma_f32 v13, v49, v13, v32
	v_fmac_f32_e32 v86, v26, v12
	v_add_f32_e32 v103, v103, v107
	v_fma_f32 v14, v50, v14, v32
	v_fmac_f32_e32 v86, v27, v13
	v_fma_f32 v15, v51, v15, v32
	v_add_f32_e32 v100, v100, v101
	v_fmac_f32_e32 v86, v28, v14
	v_fma_f32 v16, v52, v16, v32
	v_fmac_f32_e32 v86, v29, v15
	v_add_f32_e32 v102, v102, v103
	v_fma_f32 v17, v53, v17, v32
	v_fmac_f32_e32 v86, v30, v16
	v_fmac_f32_e32 v86, v31, v17
	v_add_f32_e32 v100, v100, v102
	ds_write_b32 v96, v86 offset:16384
	v_cvt_pk_bf16_f32 v22, v100, v100
	ds_write_b16 v90, v22 offset:17664
	s_waitcnt lgkmcnt(2)
	ds_read_b128 v[24:27], v0 offset:0
	ds_read_b128 v[28:31], v0 offset:16
	s_waitcnt vmcnt(8)
	ds_read_b128 v[46:49], v0 offset:4608
	ds_read_b128 v[50:53], v0 offset:4624
	ds_read_b32 v32, v1 offset:2048
	v_sub_f32_e32 v10, v10, v34
	v_sub_f32_e32 v11, v11, v34
	v_sub_f32_e32 v12, v12, v34
	v_sub_f32_e32 v13, v13, v34
	v_sub_f32_e32 v14, v14, v34
	v_sub_f32_e32 v15, v15, v34
	v_sub_f32_e32 v16, v16, v34
	v_sub_f32_e32 v17, v17, v34
	v_fma_f32 v10, v54, v10, v34
	v_fma_f32 v11, v55, v11, v34
	v_mul_f32_e32 v87, v38, v10
	v_fma_f32 v12, v56, v12, v34
	v_fmac_f32_e32 v87, v39, v11
	v_fma_f32 v13, v57, v13, v34
	v_fmac_f32_e32 v87, v40, v12
	v_fma_f32 v14, v58, v14, v34
	v_fmac_f32_e32 v87, v41, v13
	v_fma_f32 v15, v59, v15, v34
	v_fmac_f32_e32 v87, v42, v14
	v_fma_f32 v16, v60, v16, v34
	v_fmac_f32_e32 v87, v43, v15
	v_fma_f32 v17, v61, v17, v34
	v_fmac_f32_e32 v87, v44, v16
	v_fmac_f32_e32 v87, v45, v17
	ds_write_b32 v96, v87 offset:16640
	s_sub_u32 s12, s12, 1
	s_cmp_lg_u32 s12, 0
	s_cbranch_scc1 .Lls2_8_loop
	ds_read_b128 v[100:103], v97 offset:14848
	ds_read_b128 v[104:107], v98 offset:14848
	s_waitcnt lgkmcnt(0)
	v_add_f32_e32 v100, v100, v104
	v_add_f32_e32 v101, v101, v105
	v_add_f32_e32 v102, v102, v106
	v_add_f32_e32 v103, v103, v107
	v_add_f32_e32 v100, v100, v101
	v_add_f32_e32 v102, v102, v103
	v_add_f32_e32 v100, v100, v102
	v_cvt_pk_bf16_f32 v22, v100, v100
	ds_write_b16 v90, v22 offset:17792
	s_waitcnt lgkmcnt(0)
	ds_read_b128 v[92:95], v91 offset:17408
	s_waitcnt lgkmcnt(0)
	global_store_dwordx4 v7, v[92:95], s[94:95]
	v_add_u32_e32 v7, 0x20000, v7
	s_nop 0
	ds_read_b128 v[92:95], v91 offset:18432
	s_waitcnt lgkmcnt(0)
	global_store_dwordx4 v7, v[92:95], s[94:95]
	v_add_u32_e32 v7, 0x20000, v7
	s_nop 0
	ds_read_b128 v[92:95], v91 offset:19456
	s_waitcnt lgkmcnt(0)
	global_store_dwordx4 v7, v[92:95], s[94:95]
	v_add_u32_e32 v7, 0x20000, v7
	s_nop 0
	ds_read_b128 v[92:95], v91 offset:20480
	s_waitcnt lgkmcnt(0)
	global_store_dwordx4 v7, v[92:95], s[94:95]
	v_add_u32_e32 v7, 0x20000, v7
	s_nop 0
	global_store_dword v89, v10, s[26:27] offset:0
	global_store_dword v89, v11, s[26:27] offset:256
	global_store_dword v89, v12, s[26:27] offset:512
	global_store_dword v89, v13, s[26:27] offset:768
	global_store_dword v89, v14, s[26:27] offset:1024
	global_store_dword v89, v15, s[26:27] offset:1280
	global_store_dword v89, v16, s[26:27] offset:1536
	global_store_dword v89, v17, s[26:27] offset:1792
	s_waitcnt vmcnt(0) lgkmcnt(0)
	s_setprio 0
	s_branch .Lls_done
.Lls1_8_entry:
	v_and_b32_e32 v98, 63, v196
	v_and_b32_e32 v99, 7, v98
	v_lshrrev_b32_e32 v100, 3, v98
	s_min_u32 s29, s0, 4
	s_mul_i32 s29, s29, 0x5600
	v_and_b32_e32 v101, 3, v99
	v_cmp_eq_u32_e64 s[6:7], 1, v101
	v_cmp_eq_u32_e64 s[8:9], 2, v101
	v_cmp_eq_u32_e64 s[10:11], 3, v101
	v_lshl_add_u32 v0, v99, 4, s29
	v_lshl_add_u32 v1, v100, 2, s29
	s_lshl_b32 s37, s16, 11
	v_lshrrev_b32_e32 v99, 3, v98
	v_and_b32_e32 v100, 7, v98
	v_add_u32_e32 v101, s37, v99
	s_lshl_b32 s21, s17, 7
	s_add_u32 s21, s21, 0x13e00000
	v_mul_u32_u24_e32 v8, 0x630, v101
	v_lshl_add_u32 v8, v100, 4, v8
	v_add_u32_e32 v8, s21, v8
	v_lshlrev_b32_e32 v103, 7, v99
	v_lshl_add_u32 v103, v100, 4, v103
	v_add_u32_e32 v103, s29, v103
	v_and_b32_e32 v99, 31, v98
	v_lshrrev_b32_e32 v100, 2, v99
	v_and_b32_e32 v99, 3, v99
	v_add_u32_e32 v101, s37, v100
	v_cmp_gt_u32_e32 vcc, 32, v98
	s_lshl_b32 s21, s17, 6
	s_add_u32 s22, s21, 0x10800400
	s_add_u32 s44, s21, 0x8400900
	v_mov_b32_e32 v9, 0x2000
	v_mov_b32_e32 v18, 0xd00
	v_cndmask_b32_e32 v9, v9, v18, vcc
	v_mov_b32_e32 v5, s44
	v_mov_b32_e32 v18, s22
	v_cndmask_b32_e32 v5, v5, v18, vcc
	v_mul_lo_u32 v18, v101, v9
	v_add_u32_e32 v5, v5, v18
	v_lshl_add_u32 v5, v99, 4, v5
	v_lshlrev_b32_e32 v9, 3, v9
	v_mov_b32_e32 v2, 0
	v_mov_b32_e32 v18, 1024
	v_cndmask_b32_e32 v2, v2, v18, vcc
	v_lshl_add_u32 v2, v100, 7, v2
	v_lshl_add_u32 v2, v99, 5, v2
	v_add_u32_e32 v2, s29, v2
	v_lshrrev_b32_e32 v100, 3, v98
	v_and_b32_e32 v99, 7, v98
	v_add_u32_e32 v101, s37, v100
	s_lshl_b32 s22, s14, 3
	s_lshl_b32 s21, s17, 6
	s_add_u32 s21, s21, s22
	s_lshl_b32 s44, s21, 1
	s_add_u32 s44, s44, 0x8400a00
	v_lshlrev_b32_e32 v6, 13, v101
	v_lshlrev_b32_e32 v4, 5, v100
	v_lshl_add_u32 v4, v99, 2, v4
	v_lshl_add_u32 v6, v99, 1, v6
	v_add_u32_e32 v6, s44, v6
	v_add_u32_e32 v4, s29, v4
	v_and_b32_e32 v99, 7, v98
	v_lshrrev_b32_e32 v100, 3, v98
	v_add_u32_e32 v101, s37, v98
	v_lshlrev_b32_e32 v7, 11, v101
	s_lshl_b32 s44, s21, 1
	s_add_u32 s44, s44, 0x6300200
	v_add_u32_e32 v7, s44, v7
	s_lshl_b32 s44, s28, 3
	s_add_u32 s44, s44, s16
	s_lshl_b32 s44, s44, 2
	s_add_u32 s44, s44, s17
	s_mul_i32 s44, s44, 0x2000
	s_add_u32 s44, s44, 0x4300000
	s_lshl_b32 s24, s22, 2
	s_add_u32 s44, s44, s24
	v_lshlrev_b32_e32 v104, 10, v99
	v_lshl_add_u32 v104, v100, 2, v104
	v_add_u32_e32 v104, s44, v104
	v_readlane_b32 s26, v253, 29
	v_readlane_b32 s27, v253, 30
	v_lshlrev_b32_e32 v105, 4, v99
	v_lshl_add_u32 v105, v100, 1, v105
	v_add_u32_e32 v105, s29, v105
	v_lshl_add_u32 v106, v98, 4, s29
	v_lshl_add_u32 v107, v98, 2, s29
	v_lshl_add_u32 v105, v98, 1, s29
	v_subrev_u32_e32 v105, 0x200, v105
	v_lshrrev_b32_e32 v99, 3, v98
	v_and_b32_e32 v100, 7, v98
	v_lshlrev_b32_e32 v101, 8, v99
	v_lshl_add_u32 v101, v100, 5, v101
	v_add_u32_e32 v101, s29, v101
	v_bfe_u32 v99, v99, 1, 1
	v_xor_b32_e32 v100, 0, v99
	v_lshl_add_u32 v112, v100, 4, v101
	v_xor_b32_e32 v100, 1, v99
	v_lshl_add_u32 v113, v100, 4, v101
	v_mov_b32_e32 v10, 0
	v_mov_b32_e32 v11, 0
	v_mov_b32_e32 v12, 0
	v_mov_b32_e32 v13, 0
	v_mov_b32_e32 v14, 0
	v_mov_b32_e32 v15, 0
	v_mov_b32_e32 v16, 0
	v_mov_b32_e32 v17, 0
	v_mov_b32_e32 v61, 0
	v_mov_b32_e32 v102, 0
	s_setprio 2
	s_movk_i32 s12, 64
	s_nop 0
	global_load_dwordx4 v[78:81], v5, s[94:95]
	global_load_ushort v36, v6, s[94:95]
	v_add_u32_e32 v5, v5, v9
	v_add_u32_e32 v6, 0x10000, v6
	s_waitcnt vmcnt(0)
	s_waitcnt vmcnt(1)
	v_lshlrev_b32_e32 v94, 16, v78
	v_and_b32_e32 v95, 0xffff0000, v78
	v_lshlrev_b32_e32 v96, 16, v79
	v_and_b32_e32 v97, 0xffff0000, v79
	ds_write_b128 v2, v[94:97] offset:0
	v_lshlrev_b32_e32 v98, 16, v80
	v_and_b32_e32 v99, 0xffff0000, v80
	v_lshlrev_b32_e32 v100, 16, v81
	v_and_b32_e32 v101, 0xffff0000, v81
	ds_write_b128 v2, v[98:101] offset:16
	s_waitcnt vmcnt(0)
	v_lshlrev_b32_e32 v36, 16, v36
	s_nop 0
	ds_write_b32 v4, v36 offset:2048
	global_load_dwordx4 v[82:85], v5, s[94:95]
	global_load_ushort v55, v6, s[94:95]
	v_add_u32_e32 v5, v5, v9
	v_add_u32_e32 v6, 0x10000, v6
	global_load_dwordx4 v[86:89], v5, s[94:95]
	global_load_ushort v57, v6, s[94:95]
	v_add_u32_e32 v5, v5, v9
	v_add_u32_e32 v6, 0x10000, v6
	s_add_i32 m0, s29, 0x1200
	s_nop 0
	global_load_lds_dwordx4 v8, s[94:95]
	v_add_u32_e32 v8, 0x3180, v8
	global_load_dwordx4 v[90:93], v5, s[94:95]
	global_load_ushort v59, v6, s[94:95]
	v_add_u32_e32 v5, v5, v9
	v_add_u32_e32 v6, 0x10000, v6
	s_add_i32 m0, s29, 0x1600
	s_nop 0
	global_load_lds_dwordx4 v8, s[94:95]
	v_add_u32_e32 v8, 0x3180, v8
	global_load_dwordx4 v[78:81], v5, s[94:95]
	global_load_ushort v36, v6, s[94:95]
	v_add_u32_e32 v5, v5, v9
	v_add_u32_e32 v6, 0x10000, v6
	s_add_i32 m0, s29, 0x1a00
	s_nop 0
	global_load_lds_dwordx4 v8, s[94:95]
	v_add_u32_e32 v8, 0x3180, v8
	ds_read_b128 v[20:23], v0 offset:0
	ds_read_b128 v[38:41], v0 offset:1024
	s_waitcnt vmcnt(6)
	ds_read_b128 v[62:65], v0 offset:4608
	ds_read_b32 v54, v1 offset:2048
	ds_read_b128 v[24:27], v0 offset:128
	ds_read_b128 v[42:45], v0 offset:1152
	ds_read_b128 v[66:69], v0 offset:4736
	ds_read_b32 v56, v1 offset:2080
	ds_read_b128 v[28:31], v0 offset:256
	ds_read_b128 v[46:49], v0 offset:1280
	ds_read_b128 v[70:73], v0 offset:4864
	ds_read_b32 v58, v1 offset:2112
.Lls1_8_loop:
	s_waitcnt lgkmcnt(8)
	v_mul_f32_e32 v10, v62, v10
	v_mul_f32_e32 v11, v63, v11
	v_mul_f32_e32 v12, v64, v12
	s_waitcnt vmcnt(10)
	v_mul_f32_e32 v13, v65, v13
	v_fmac_f32_e32 v10, v20, v54
	v_fmac_f32_e32 v11, v21, v54
	v_lshlrev_b32_e32 v94, 16, v82
	v_mul_f32_e32 v61, v38, v10
	v_fmac_f32_e32 v12, v22, v54
	v_fmac_f32_e32 v61, v39, v11
	v_and_b32_e32 v95, 0xffff0000, v82
	v_fmac_f32_e32 v13, v23, v54
	v_fmac_f32_e32 v61, v40, v12
	v_fmac_f32_e32 v61, v41, v13
	v_lshlrev_b32_e32 v96, 16, v83
	ds_write_b32 v107, v61 offset:8704
	ds_read_b128 v[32:35], v0 offset:384
	ds_read_b128 v[50:53], v0 offset:1408
	ds_read_b128 v[74:77], v0 offset:4992
	ds_read_b32 v60, v1 offset:2144
	s_waitcnt lgkmcnt(9)
	v_mul_f32_e32 v10, v66, v10
	v_mul_f32_e32 v11, v67, v11
	v_mul_f32_e32 v12, v68, v12
	v_and_b32_e32 v97, 0xffff0000, v83
	v_mul_f32_e32 v13, v69, v13
	v_fmac_f32_e32 v10, v24, v56
	v_fmac_f32_e32 v11, v25, v56
	ds_write_b128 v2, v[94:97] offset:2304
	v_mul_f32_e32 v102, v42, v10
	v_fmac_f32_e32 v12, v26, v56
	v_fmac_f32_e32 v102, v43, v11
	v_lshlrev_b32_e32 v98, 16, v84
	v_fmac_f32_e32 v13, v27, v56
	v_fmac_f32_e32 v102, v44, v12
	v_fmac_f32_e32 v102, v45, v13
	v_and_b32_e32 v99, 0xffff0000, v84
	ds_write_b32 v107, v102 offset:8960
	ds_read_b128 v[20:23], v0 offset:512
	ds_read_b128 v[38:41], v0 offset:1536
	ds_read_b128 v[62:65], v0 offset:5120
	ds_read_b32 v54, v1 offset:2176
	s_waitcnt lgkmcnt(11)
	v_mul_f32_e32 v10, v70, v10
	v_mul_f32_e32 v11, v71, v11
	v_mul_f32_e32 v12, v72, v12
	v_lshlrev_b32_e32 v100, 16, v85
	v_mul_f32_e32 v13, v73, v13
	v_fmac_f32_e32 v10, v28, v58
	v_fmac_f32_e32 v11, v29, v58
	v_and_b32_e32 v101, 0xffff0000, v85
	v_mul_f32_e32 v61, v46, v10
	v_fmac_f32_e32 v12, v30, v58
	v_fmac_f32_e32 v61, v47, v11
	ds_write_b128 v2, v[98:101] offset:2320
	v_fmac_f32_e32 v13, v31, v58
	v_fmac_f32_e32 v61, v48, v12
	v_fmac_f32_e32 v61, v49, v13
	s_waitcnt vmcnt(9)
	ds_write_b32 v107, v61 offset:9216
	ds_read_b128 v[24:27], v0 offset:640
	ds_read_b128 v[42:45], v0 offset:1664
	ds_read_b128 v[66:69], v0 offset:5248
	ds_read_b32 v56, v1 offset:2208
	s_waitcnt lgkmcnt(12)
	v_mul_f32_e32 v10, v74, v10
	v_mul_f32_e32 v11, v75, v11
	v_mul_f32_e32 v12, v76, v12
	v_lshlrev_b32_e32 v55, 16, v55
	v_mul_f32_e32 v13, v77, v13
	v_fmac_f32_e32 v10, v32, v60
	v_fmac_f32_e32 v11, v33, v60
	s_nop 0
	v_mul_f32_e32 v102, v50, v10
	v_fmac_f32_e32 v12, v34, v60
	v_fmac_f32_e32 v102, v51, v11
	ds_write_b32 v4, v55 offset:4352
	v_fmac_f32_e32 v13, v35, v60
	v_fmac_f32_e32 v102, v52, v12
	v_fmac_f32_e32 v102, v53, v13
	ds_read_b128 v[28:31], v0 offset:768
	ds_write_b32 v107, v102 offset:9472
	ds_read_b128 v[46:49], v0 offset:1792
	ds_read_b128 v[70:73], v0 offset:5376
	ds_read_b32 v58, v1 offset:2240
	s_waitcnt lgkmcnt(12)
	v_mul_f32_e32 v10, v62, v10
	v_mul_f32_e32 v11, v63, v11
	v_mul_f32_e32 v12, v64, v12
	global_load_dwordx4 v[82:85], v5, s[94:95]
	global_load_ushort v55, v6, s[94:95]
	v_add_u32_e32 v5, v5, v9
	v_add_u32_e32 v6, 0x10000, v6
	v_mul_f32_e32 v13, v65, v13
	v_fmac_f32_e32 v10, v20, v54
	v_fmac_f32_e32 v11, v21, v54
	s_add_i32 m0, s29, 0x1e00
	s_nop 0
	global_load_lds_dwordx4 v8, s[94:95]
	v_add_u32_e32 v8, 0x3180, v8
	v_mul_f32_e32 v61, v38, v10
	v_fmac_f32_e32 v12, v22, v54
	v_fmac_f32_e32 v61, v39, v11
	ds_read_b128 v[114:117], v112 offset:10752
	v_fmac_f32_e32 v13, v23, v54
	v_fmac_f32_e32 v61, v40, v12
	v_fmac_f32_e32 v61, v41, v13
	ds_read_b128 v[118:121], v113 offset:10752
	ds_write_b32 v107, v61 offset:9728
	ds_read_b128 v[32:35], v0 offset:896
	ds_read_b128 v[50:53], v0 offset:1920
	ds_read_b128 v[74:77], v0 offset:5504
	ds_read_b32 v60, v1 offset:2272
	s_waitcnt lgkmcnt(13)
	v_mul_f32_e32 v10, v66, v10
	v_mul_f32_e32 v11, v67, v11
	v_mul_f32_e32 v12, v68, v12
	ds_read_b128 v[20:23], v0 offset:2304
	v_mul_f32_e32 v13, v69, v13
	v_fmac_f32_e32 v10, v24, v56
	v_fmac_f32_e32 v11, v25, v56
	ds_read_b128 v[38:41], v0 offset:3328
	v_mul_f32_e32 v102, v42, v10
	v_fmac_f32_e32 v12, v26, v56
	v_fmac_f32_e32 v102, v43, v11
	s_waitcnt vmcnt(6)
	v_fmac_f32_e32 v13, v27, v56
	v_fmac_f32_e32 v102, v44, v12
	v_fmac_f32_e32 v102, v45, v13
	ds_read_b128 v[62:65], v0 offset:5632
	ds_write_b32 v107, v102 offset:9984
	ds_read_b32 v54, v1 offset:4352
	s_waitcnt lgkmcnt(12)
	v_mul_f32_e32 v10, v70, v10
	v_mul_f32_e32 v11, v71, v11
	v_mul_f32_e32 v12, v72, v12
	s_waitcnt lgkmcnt(10)
	v_mul_f32_e32 v13, v73, v13
	v_fmac_f32_e32 v10, v28, v58
	v_fmac_f32_e32 v11, v29, v58
	v_add_f32_e32 v114, v114, v118
	v_mul_f32_e32 v61, v46, v10
	v_fmac_f32_e32 v12, v30, v58
	v_fmac_f32_e32 v61, v47, v11
	v_add_f32_e32 v115, v115, v119
	v_fmac_f32_e32 v13, v31, v58
	v_fmac_f32_e32 v61, v48, v12
	v_fmac_f32_e32 v61, v49, v13
	v_add_f32_e32 v116, v116, v120
	ds_write_b32 v107, v61 offset:10240
	ds_read_b128 v[24:27], v0 offset:2432
	ds_read_b128 v[42:45], v0 offset:3456
	ds_read_b128 v[66:69], v0 offset:5760
	ds_read_b32 v56, v1 offset:4384
	v_add_f32_e32 v117, v117, v121
	v_add_f32_e32 v114, v114, v115
	v_add_f32_e32 v116, v116, v117
	v_add_f32_e32 v114, v114, v116
	v_cvt_pk_bf16_f32 v19, v114, v114
	ds_write_b16 v105, v19 offset:13696
	v_add_u32_e32 v105, 0x200, v105
	s_and_b32 s24, s12, 15
	s_cmp_eq_u32 s24, 0
	s_cbranch_scc0 .Lls1_8_noflush
	s_cmp_eq_u32 s12, 64
	s_cbranch_scc1 .Lls1_8_noflush
	s_waitcnt lgkmcnt(0)
	ds_read_b128 v[108:111], v106 offset:13312
	s_waitcnt lgkmcnt(0)
	global_store_dwordx4 v7, v[108:111], s[94:95]
	v_add_u32_e32 v7, 0x20000, v7
	s_nop 0
	ds_read_b128 v[108:111], v106 offset:14336
	s_waitcnt lgkmcnt(0)
	global_store_dwordx4 v7, v[108:111], s[94:95]
	v_add_u32_e32 v7, 0x20000, v7
	s_nop 0
	ds_read_b128 v[108:111], v106 offset:15360
	s_waitcnt lgkmcnt(0)
	global_store_dwordx4 v7, v[108:111], s[94:95]
	v_add_u32_e32 v7, 0x20000, v7
	s_nop 0
	ds_read_b128 v[108:111], v106 offset:16384
	s_waitcnt lgkmcnt(0)
	global_store_dwordx4 v7, v[108:111], s[94:95]
	v_add_u32_e32 v7, 0x20000, v7
	s_nop 0
	ds_read_b128 v[108:111], v106 offset:17408
	s_waitcnt lgkmcnt(0)
	global_store_dwordx4 v7, v[108:111], s[94:95]
	v_add_u32_e32 v7, 0x20000, v7
	s_nop 0
	ds_read_b128 v[108:111], v106 offset:18432
	s_waitcnt lgkmcnt(0)
	global_store_dwordx4 v7, v[108:111], s[94:95]
	v_add_u32_e32 v7, 0x20000, v7
	s_nop 0
	ds_read_b128 v[108:111], v106 offset:19456
	s_waitcnt lgkmcnt(0)
	global_store_dwordx4 v7, v[108:111], s[94:95]
	v_add_u32_e32 v7, 0x20000, v7
	s_nop 0
	ds_read_b128 v[108:111], v106 offset:20480
	s_waitcnt lgkmcnt(0)
	global_store_dwordx4 v7, v[108:111], s[94:95]
	v_add_u32_e32 v7, 0x20000, v7
	s_nop 0
	v_subrev_u32_e32 v105, 0x2000, v105
.Lls1_8_noflush:
	s_waitcnt lgkmcnt(11)
	v_mul_f32_e32 v10, v74, v10
	v_mul_f32_e32 v11, v75, v11
	v_mul_f32_e32 v12, v76, v12
	ds_read_b128 v[28:31], v0 offset:2560
	v_mul_f32_e32 v13, v77, v13
	v_fmac_f32_e32 v10, v32, v60
	v_fmac_f32_e32 v11, v33, v60
	ds_read_b128 v[46:49], v0 offset:3584
	v_mul_f32_e32 v102, v50, v10
	v_fmac_f32_e32 v12, v34, v60
	v_fmac_f32_e32 v102, v51, v11
	ds_read_b128 v[70:73], v0 offset:5888
	v_fmac_f32_e32 v13, v35, v60
	v_fmac_f32_e32 v102, v52, v12
	v_fmac_f32_e32 v102, v53, v13
	ds_read_b32 v58, v1 offset:4416
	ds_write_b32 v107, v102 offset:10496
	s_waitcnt lgkmcnt(11)
	v_mul_f32_e32 v10, v62, v10
	v_mul_f32_e32 v11, v63, v11
	v_mul_f32_e32 v12, v64, v12
	s_waitcnt vmcnt(11)
	v_mul_f32_e32 v13, v65, v13
	v_fmac_f32_e32 v10, v20, v54
	v_fmac_f32_e32 v11, v21, v54
	v_lshlrev_b32_e32 v94, 16, v86
	v_mul_f32_e32 v61, v38, v10
	v_fmac_f32_e32 v12, v22, v54
	v_fmac_f32_e32 v61, v39, v11
	v_and_b32_e32 v95, 0xffff0000, v86
	v_fmac_f32_e32 v13, v23, v54
	v_fmac_f32_e32 v61, v40, v12
	v_fmac_f32_e32 v61, v41, v13
	v_lshlrev_b32_e32 v96, 16, v87
	ds_write_b32 v107, v61 offset:10752
	ds_read_b128 v[32:35], v0 offset:2688
	ds_read_b128 v[50:53], v0 offset:3712
	ds_read_b128 v[74:77], v0 offset:6016
	ds_read_b32 v60, v1 offset:4448
	s_waitcnt lgkmcnt(11)
	v_mul_f32_e32 v10, v66, v10
	v_mul_f32_e32 v11, v67, v11
	v_mul_f32_e32 v12, v68, v12
	v_and_b32_e32 v97, 0xffff0000, v87
	v_mul_f32_e32 v13, v69, v13
	v_fmac_f32_e32 v10, v24, v56
	v_fmac_f32_e32 v11, v25, v56
	ds_write_b128 v2, v[94:97] offset:0
	v_mul_f32_e32 v102, v42, v10
	v_fmac_f32_e32 v12, v26, v56
	v_fmac_f32_e32 v102, v43, v11
	v_lshlrev_b32_e32 v98, 16, v88
	v_fmac_f32_e32 v13, v27, v56
	v_fmac_f32_e32 v102, v44, v12
	v_fmac_f32_e32 v102, v45, v13
	v_and_b32_e32 v99, 0xffff0000, v88
	ds_write_b32 v107, v102 offset:11008
	ds_read_b128 v[20:23], v0 offset:2816
	ds_read_b128 v[38:41], v0 offset:3840
	ds_read_b128 v[62:65], v0 offset:6144
	ds_read_b32 v54, v1 offset:4480
	s_waitcnt lgkmcnt(12)
	v_mul_f32_e32 v10, v70, v10
	v_mul_f32_e32 v11, v71, v11
	v_mul_f32_e32 v12, v72, v12
	v_lshlrev_b32_e32 v100, 16, v89
	v_mul_f32_e32 v13, v73, v13
	v_fmac_f32_e32 v10, v28, v58
	v_fmac_f32_e32 v11, v29, v58
	v_and_b32_e32 v101, 0xffff0000, v89
	v_mul_f32_e32 v61, v46, v10
	v_fmac_f32_e32 v12, v30, v58
	v_fmac_f32_e32 v61, v47, v11
	ds_write_b128 v2, v[98:101] offset:16
	v_fmac_f32_e32 v13, v31, v58
	v_fmac_f32_e32 v61, v48, v12
	v_fmac_f32_e32 v61, v49, v13
	s_waitcnt vmcnt(10)
	ds_write_b32 v107, v61 offset:11264
	ds_read_b128 v[24:27], v0 offset:2944
	ds_read_b128 v[42:45], v0 offset:3968
	ds_read_b128 v[66:69], v0 offset:6272
	ds_read_b32 v56, v1 offset:4512
	s_waitcnt lgkmcnt(12)
	v_mul_f32_e32 v10, v74, v10
	v_mul_f32_e32 v11, v75, v11
	v_mul_f32_e32 v12, v76, v12
	v_lshlrev_b32_e32 v57, 16, v57
	v_mul_f32_e32 v13, v77, v13
	v_fmac_f32_e32 v10, v32, v60
	v_fmac_f32_e32 v11, v33, v60
	s_nop 0
	v_mul_f32_e32 v102, v50, v10
	v_fmac_f32_e32 v12, v34, v60
	v_fmac_f32_e32 v102, v51, v11
	ds_write_b32 v4, v57 offset:2048
	v_fmac_f32_e32 v13, v35, v60
	v_fmac_f32_e32 v102, v52, v12
	v_fmac_f32_e32 v102, v53, v13
	ds_read_b128 v[28:31], v0 offset:3072
	ds_write_b32 v107, v102 offset:11520
	ds_read_b128 v[46:49], v0 offset:4096
	ds_read_b128 v[70:73], v0 offset:6400
	ds_read_b32 v58, v1 offset:4544
	s_waitcnt lgkmcnt(12)
	v_mul_f32_e32 v10, v62, v10
	v_mul_f32_e32 v11, v63, v11
	v_mul_f32_e32 v12, v64, v12
	global_load_dwordx4 v[86:89], v5, s[94:95]
	global_load_ushort v57, v6, s[94:95]
	v_add_u32_e32 v5, v5, v9
	v_add_u32_e32 v6, 0x10000, v6
	v_mul_f32_e32 v13, v65, v13
	v_fmac_f32_e32 v10, v20, v54
	v_fmac_f32_e32 v11, v21, v54
	s_add_i32 m0, s29, 0x1200
	s_nop 0
	global_load_lds_dwordx4 v8, s[94:95]
	v_add_u32_e32 v8, 0x3180, v8
	v_mul_f32_e32 v61, v38, v10
	v_fmac_f32_e32 v12, v22, v54
	v_fmac_f32_e32 v61, v39, v11
	ds_read_b128 v[114:117], v112 offset:8704
	v_fmac_f32_e32 v13, v23, v54
	v_fmac_f32_e32 v61, v40, v12
	v_fmac_f32_e32 v61, v41, v13
	ds_read_b128 v[118:121], v113 offset:8704
	ds_write_b32 v107, v61 offset:11776
	ds_read_b128 v[32:35], v0 offset:3200
	ds_read_b128 v[50:53], v0 offset:4224
	ds_read_b128 v[74:77], v0 offset:6528
	ds_read_b32 v60, v1 offset:4576
	s_waitcnt lgkmcnt(13)
	v_mul_f32_e32 v10, v66, v10
	v_mul_f32_e32 v11, v67, v11
	v_mul_f32_e32 v12, v68, v12
	ds_read_b128 v[20:23], v0 offset:0
	v_mul_f32_e32 v13, v69, v13
	v_fmac_f32_e32 v10, v24, v56
	v_fmac_f32_e32 v11, v25, v56
	ds_read_b128 v[38:41], v0 offset:1024
	v_mul_f32_e32 v102, v42, v10
	v_fmac_f32_e32 v12, v26, v56
	v_fmac_f32_e32 v102, v43, v11
	s_waitcnt vmcnt(6)
	v_fmac_f32_e32 v13, v27, v56
	v_fmac_f32_e32 v102, v44, v12
	v_fmac_f32_e32 v102, v45, v13
	ds_read_b128 v[62:65], v0 offset:6656
	ds_write_b32 v107, v102 offset:12032
	ds_read_b32 v54, v1 offset:2048
	s_waitcnt lgkmcnt(12)
	v_mul_f32_e32 v10, v70, v10
	v_mul_f32_e32 v11, v71, v11
	v_mul_f32_e32 v12, v72, v12
	s_waitcnt lgkmcnt(10)
	v_mul_f32_e32 v13, v73, v13
	v_fmac_f32_e32 v10, v28, v58
	v_fmac_f32_e32 v11, v29, v58
	v_add_f32_e32 v114, v114, v118
	v_mul_f32_e32 v61, v46, v10
	v_fmac_f32_e32 v12, v30, v58
	v_fmac_f32_e32 v61, v47, v11
	v_add_f32_e32 v115, v115, v119
	v_fmac_f32_e32 v13, v31, v58
	v_fmac_f32_e32 v61, v48, v12
	v_fmac_f32_e32 v61, v49, v13
	v_add_f32_e32 v116, v116, v120
	ds_write_b32 v107, v61 offset:12288
	ds_read_b128 v[24:27], v0 offset:128
	ds_read_b128 v[42:45], v0 offset:1152
	ds_read_b128 v[66:69], v0 offset:6784
	ds_read_b32 v56, v1 offset:2080
	v_add_f32_e32 v117, v117, v121
	v_add_f32_e32 v114, v114, v115
	v_add_f32_e32 v116, v116, v117
	v_add_f32_e32 v114, v114, v116
	v_cvt_pk_bf16_f32 v19, v114, v114
	ds_write_b16 v105, v19 offset:13312
	s_waitcnt lgkmcnt(11)
	v_mul_f32_e32 v10, v74, v10
	v_mul_f32_e32 v11, v75, v11
	v_mul_f32_e32 v12, v76, v12
	ds_read_b128 v[28:31], v0 offset:256
	v_mul_f32_e32 v13, v77, v13
	v_fmac_f32_e32 v10, v32, v60
	v_fmac_f32_e32 v11, v33, v60
	ds_read_b128 v[46:49], v0 offset:1280
	v_mul_f32_e32 v102, v50, v10
	v_fmac_f32_e32 v12, v34, v60
	v_fmac_f32_e32 v102, v51, v11
	ds_read_b128 v[70:73], v0 offset:6912
	v_fmac_f32_e32 v13, v35, v60
	v_fmac_f32_e32 v102, v52, v12
	v_fmac_f32_e32 v102, v53, v13
	ds_read_b32 v58, v1 offset:2112
	ds_write_b32 v107, v102 offset:12544
	s_waitcnt lgkmcnt(11)
	v_mul_f32_e32 v10, v62, v10
	v_mul_f32_e32 v11, v63, v11
	v_mul_f32_e32 v12, v64, v12
	s_waitcnt vmcnt(11)
	v_mul_f32_e32 v13, v65, v13
	v_fmac_f32_e32 v10, v20, v54
	v_fmac_f32_e32 v11, v21, v54
	v_lshlrev_b32_e32 v94, 16, v90
	v_mul_f32_e32 v61, v38, v10
	v_fmac_f32_e32 v12, v22, v54
	v_fmac_f32_e32 v61, v39, v11
	v_and_b32_e32 v95, 0xffff0000, v90
	v_fmac_f32_e32 v13, v23, v54
	v_fmac_f32_e32 v61, v40, v12
	v_fmac_f32_e32 v61, v41, v13
	v_lshlrev_b32_e32 v96, 16, v91
	ds_write_b32 v107, v61 offset:8704
	ds_read_b128 v[32:35], v0 offset:384
	ds_read_b128 v[50:53], v0 offset:1408
	ds_read_b128 v[74:77], v0 offset:7040
	ds_read_b32 v60, v1 offset:2144
	s_waitcnt lgkmcnt(11)
	v_mul_f32_e32 v10, v66, v10
	v_mul_f32_e32 v11, v67, v11
	v_mul_f32_e32 v12, v68, v12
	v_and_b32_e32 v97, 0xffff0000, v91
	v_mul_f32_e32 v13, v69, v13
	v_fmac_f32_e32 v10, v24, v56
	v_fmac_f32_e32 v11, v25, v56
	ds_write_b128 v2, v[94:97] offset:2304
	v_mul_f32_e32 v102, v42, v10
	v_fmac_f32_e32 v12, v26, v56
	v_fmac_f32_e32 v102, v43, v11
	v_lshlrev_b32_e32 v98, 16, v92
	v_fmac_f32_e32 v13, v27, v56
	v_fmac_f32_e32 v102, v44, v12
	v_fmac_f32_e32 v102, v45, v13
	v_and_b32_e32 v99, 0xffff0000, v92
	ds_write_b32 v107, v102 offset:8960
	ds_read_b128 v[20:23], v0 offset:512
	ds_read_b128 v[38:41], v0 offset:1536
	ds_read_b128 v[62:65], v0 offset:7168
	ds_read_b32 v54, v1 offset:2176
	s_waitcnt lgkmcnt(12)
	v_mul_f32_e32 v10, v70, v10
	v_mul_f32_e32 v11, v71, v11
	v_mul_f32_e32 v12, v72, v12
	v_lshlrev_b32_e32 v100, 16, v93
	v_mul_f32_e32 v13, v73, v13
	v_fmac_f32_e32 v10, v28, v58
	v_fmac_f32_e32 v11, v29, v58
	v_and_b32_e32 v101, 0xffff0000, v93
	v_mul_f32_e32 v61, v46, v10
	v_fmac_f32_e32 v12, v30, v58
	v_fmac_f32_e32 v61, v47, v11
	ds_write_b128 v2, v[98:101] offset:2320
	v_fmac_f32_e32 v13, v31, v58
	v_fmac_f32_e32 v61, v48, v12
	v_fmac_f32_e32 v61, v49, v13
	s_waitcnt vmcnt(10)
	ds_write_b32 v107, v61 offset:9216
	ds_read_b128 v[24:27], v0 offset:640
	ds_read_b128 v[42:45], v0 offset:1664
	ds_read_b128 v[66:69], v0 offset:7296
	ds_read_b32 v56, v1 offset:2208
	s_waitcnt lgkmcnt(12)
	v_mul_f32_e32 v10, v74, v10
	v_mul_f32_e32 v11, v75, v11
	v_mul_f32_e32 v12, v76, v12
	v_lshlrev_b32_e32 v59, 16, v59
	v_mul_f32_e32 v13, v77, v13
	v_fmac_f32_e32 v10, v32, v60
	v_fmac_f32_e32 v11, v33, v60
	s_nop 0
	v_mul_f32_e32 v102, v50, v10
	v_fmac_f32_e32 v12, v34, v60
	v_fmac_f32_e32 v102, v51, v11
	ds_write_b32 v4, v59 offset:4352
	v_fmac_f32_e32 v13, v35, v60
	v_fmac_f32_e32 v102, v52, v12
	v_fmac_f32_e32 v102, v53, v13
	ds_read_b128 v[28:31], v0 offset:768
	ds_write_b32 v107, v102 offset:9472
	ds_read_b128 v[46:49], v0 offset:1792
	ds_read_b128 v[70:73], v0 offset:7424
	ds_read_b32 v58, v1 offset:2240
	s_waitcnt lgkmcnt(12)
	v_mul_f32_e32 v10, v62, v10
	v_mul_f32_e32 v11, v63, v11
	v_mul_f32_e32 v12, v64, v12
	global_load_dwordx4 v[90:93], v5, s[94:95]
	global_load_ushort v59, v6, s[94:95]
	v_add_u32_e32 v5, v5, v9
	v_add_u32_e32 v6, 0x10000, v6
	v_mul_f32_e32 v13, v65, v13
	v_fmac_f32_e32 v10, v20, v54
	v_fmac_f32_e32 v11, v21, v54
	s_add_i32 m0, s29, 0x1600
	s_nop 0
	global_load_lds_dwordx4 v8, s[94:95]
	v_add_u32_e32 v8, 0x3180, v8
	v_mul_f32_e32 v61, v38, v10
	v_fmac_f32_e32 v12, v22, v54
	v_fmac_f32_e32 v61, v39, v11
	ds_read_b128 v[114:117], v112 offset:10752
	v_fmac_f32_e32 v13, v23, v54
	v_fmac_f32_e32 v61, v40, v12
	v_fmac_f32_e32 v61, v41, v13
	ds_read_b128 v[118:121], v113 offset:10752
	ds_write_b32 v107, v61 offset:9728
	ds_read_b128 v[32:35], v0 offset:896
	ds_read_b128 v[50:53], v0 offset:1920
	ds_read_b128 v[74:77], v0 offset:7552
	ds_read_b32 v60, v1 offset:2272
	s_waitcnt lgkmcnt(13)
	v_mul_f32_e32 v10, v66, v10
	v_mul_f32_e32 v11, v67, v11
	v_mul_f32_e32 v12, v68, v12
	ds_read_b128 v[20:23], v0 offset:2304
	v_mul_f32_e32 v13, v69, v13
	v_fmac_f32_e32 v10, v24, v56
	v_fmac_f32_e32 v11, v25, v56
	ds_read_b128 v[38:41], v0 offset:3328
	v_mul_f32_e32 v102, v42, v10
	v_fmac_f32_e32 v12, v26, v56
	v_fmac_f32_e32 v102, v43, v11
	s_waitcnt vmcnt(6)
	v_fmac_f32_e32 v13, v27, v56
	v_fmac_f32_e32 v102, v44, v12
	v_fmac_f32_e32 v102, v45, v13
	ds_read_b128 v[62:65], v0 offset:7680
	ds_write_b32 v107, v102 offset:9984
	ds_read_b32 v54, v1 offset:4352
	s_waitcnt lgkmcnt(12)
	v_mul_f32_e32 v10, v70, v10
	v_mul_f32_e32 v11, v71, v11
	v_mul_f32_e32 v12, v72, v12
	s_waitcnt lgkmcnt(10)
	v_mul_f32_e32 v13, v73, v13
	v_fmac_f32_e32 v10, v28, v58
	v_fmac_f32_e32 v11, v29, v58
	v_add_f32_e32 v114, v114, v118
	v_mul_f32_e32 v61, v46, v10
	v_fmac_f32_e32 v12, v30, v58
	v_fmac_f32_e32 v61, v47, v11
	v_add_f32_e32 v115, v115, v119
	v_fmac_f32_e32 v13, v31, v58
	v_fmac_f32_e32 v61, v48, v12
	v_fmac_f32_e32 v61, v49, v13
	v_add_f32_e32 v116, v116, v120
	ds_write_b32 v107, v61 offset:10240
	ds_read_b128 v[24:27], v0 offset:2432
	ds_read_b128 v[42:45], v0 offset:3456
	ds_read_b128 v[66:69], v0 offset:7808
	ds_read_b32 v56, v1 offset:4384
	v_add_f32_e32 v117, v117, v121
	v_add_f32_e32 v114, v114, v115
	v_add_f32_e32 v116, v116, v117
	v_add_f32_e32 v114, v114, v116
	v_cvt_pk_bf16_f32 v19, v114, v114
	ds_write_b16 v105, v19 offset:13440
	s_waitcnt lgkmcnt(11)
	v_mul_f32_e32 v10, v74, v10
	v_mul_f32_e32 v11, v75, v11
	v_mul_f32_e32 v12, v76, v12
	ds_read_b128 v[28:31], v0 offset:2560
	v_mul_f32_e32 v13, v77, v13
	v_fmac_f32_e32 v10, v32, v60
	v_fmac_f32_e32 v11, v33, v60
	ds_read_b128 v[46:49], v0 offset:3584
	v_mul_f32_e32 v102, v50, v10
	v_fmac_f32_e32 v12, v34, v60
	v_fmac_f32_e32 v102, v51, v11
	ds_read_b128 v[70:73], v0 offset:7936
	v_fmac_f32_e32 v13, v35, v60
	v_fmac_f32_e32 v102, v52, v12
	v_fmac_f32_e32 v102, v53, v13
	ds_read_b32 v58, v1 offset:4416
	ds_write_b32 v107, v102 offset:10496
	s_waitcnt lgkmcnt(11)
	v_mul_f32_e32 v10, v62, v10
	v_mul_f32_e32 v11, v63, v11
	v_mul_f32_e32 v12, v64, v12
	s_waitcnt vmcnt(11)
	v_mul_f32_e32 v13, v65, v13
	v_fmac_f32_e32 v10, v20, v54
	v_fmac_f32_e32 v11, v21, v54
	v_lshlrev_b32_e32 v94, 16, v78
	v_mul_f32_e32 v61, v38, v10
	v_fmac_f32_e32 v12, v22, v54
	v_fmac_f32_e32 v61, v39, v11
	v_and_b32_e32 v95, 0xffff0000, v78
	v_fmac_f32_e32 v13, v23, v54
	v_fmac_f32_e32 v61, v40, v12
	v_fmac_f32_e32 v61, v41, v13
	v_lshlrev_b32_e32 v96, 16, v79
	ds_write_b32 v107, v61 offset:10752
	ds_read_b128 v[32:35], v0 offset:2688
	ds_read_b128 v[50:53], v0 offset:3712
	ds_read_b128 v[74:77], v0 offset:8064
	ds_read_b32 v60, v1 offset:4448
	s_waitcnt lgkmcnt(11)
	v_mul_f32_e32 v10, v66, v10
	v_mul_f32_e32 v11, v67, v11
	v_mul_f32_e32 v12, v68, v12
	v_and_b32_e32 v97, 0xffff0000, v79
	v_mul_f32_e32 v13, v69, v13
	v_fmac_f32_e32 v10, v24, v56
	v_fmac_f32_e32 v11, v25, v56
	ds_write_b128 v2, v[94:97] offset:0
	v_mul_f32_e32 v102, v42, v10
	v_fmac_f32_e32 v12, v26, v56
	v_fmac_f32_e32 v102, v43, v11
	v_lshlrev_b32_e32 v98, 16, v80
	v_fmac_f32_e32 v13, v27, v56
	v_fmac_f32_e32 v102, v44, v12
	v_fmac_f32_e32 v102, v45, v13
	v_and_b32_e32 v99, 0xffff0000, v80
	ds_write_b32 v107, v102 offset:11008
	ds_read_b128 v[20:23], v0 offset:2816
	ds_read_b128 v[38:41], v0 offset:3840
	ds_read_b128 v[62:65], v0 offset:8192
	ds_read_b32 v54, v1 offset:4480
	s_waitcnt lgkmcnt(12)
	v_mul_f32_e32 v10, v70, v10
	v_mul_f32_e32 v11, v71, v11
	v_mul_f32_e32 v12, v72, v12
	v_lshlrev_b32_e32 v100, 16, v81
	v_mul_f32_e32 v13, v73, v13
	v_fmac_f32_e32 v10, v28, v58
	v_fmac_f32_e32 v11, v29, v58
	v_and_b32_e32 v101, 0xffff0000, v81
	v_mul_f32_e32 v61, v46, v10
	v_fmac_f32_e32 v12, v30, v58
	v_fmac_f32_e32 v61, v47, v11
	ds_write_b128 v2, v[98:101] offset:16
	v_fmac_f32_e32 v13, v31, v58
	v_fmac_f32_e32 v61, v48, v12
	v_fmac_f32_e32 v61, v49, v13
	s_waitcnt vmcnt(10)
	ds_write_b32 v107, v61 offset:11264
	ds_read_b128 v[24:27], v0 offset:2944
	ds_read_b128 v[42:45], v0 offset:3968
	ds_read_b128 v[66:69], v0 offset:8320
	ds_read_b32 v56, v1 offset:4512
	s_waitcnt lgkmcnt(12)
	v_mul_f32_e32 v10, v74, v10
	v_mul_f32_e32 v11, v75, v11
	v_mul_f32_e32 v12, v76, v12
	v_lshlrev_b32_e32 v36, 16, v36
	v_mul_f32_e32 v13, v77, v13
	v_fmac_f32_e32 v10, v32, v60
	v_fmac_f32_e32 v11, v33, v60
	s_nop 0
	v_mul_f32_e32 v102, v50, v10
	v_fmac_f32_e32 v12, v34, v60
	v_fmac_f32_e32 v102, v51, v11
	ds_write_b32 v4, v36 offset:2048
	v_fmac_f32_e32 v13, v35, v60
	v_fmac_f32_e32 v102, v52, v12
	v_fmac_f32_e32 v102, v53, v13
	ds_read_b128 v[28:31], v0 offset:3072
	ds_write_b32 v107, v102 offset:11520
	ds_read_b128 v[46:49], v0 offset:4096
	ds_read_b128 v[70:73], v0 offset:8448
	ds_read_b32 v58, v1 offset:4544
	s_waitcnt lgkmcnt(12)
	v_mul_f32_e32 v10, v62, v10
	v_mul_f32_e32 v11, v63, v11
	v_mul_f32_e32 v12, v64, v12
	global_load_dwordx4 v[78:81], v5, s[94:95]
	global_load_ushort v36, v6, s[94:95]
	v_add_u32_e32 v5, v5, v9
	v_add_u32_e32 v6, 0x10000, v6
	v_mul_f32_e32 v13, v65, v13
	v_fmac_f32_e32 v10, v20, v54
	v_fmac_f32_e32 v11, v21, v54
	s_add_i32 m0, s29, 0x1a00
	s_nop 0
	global_load_lds_dwordx4 v8, s[94:95]
	v_add_u32_e32 v8, 0x3180, v8
	v_mul_f32_e32 v61, v38, v10
	v_fmac_f32_e32 v12, v22, v54
	v_fmac_f32_e32 v61, v39, v11
	ds_read_b128 v[114:117], v112 offset:8704
	v_fmac_f32_e32 v13, v23, v54
	v_fmac_f32_e32 v61, v40, v12
	v_fmac_f32_e32 v61, v41, v13
	ds_read_b128 v[118:121], v113 offset:8704
	ds_write_b32 v107, v61 offset:11776
	ds_read_b128 v[32:35], v0 offset:3200
	ds_read_b128 v[50:53], v0 offset:4224
	ds_read_b128 v[74:77], v0 offset:8576
	ds_read_b32 v60, v1 offset:4576
	s_waitcnt lgkmcnt(13)
	v_mul_f32_e32 v10, v66, v10
	v_mul_f32_e32 v11, v67, v11
	v_mul_f32_e32 v12, v68, v12
	ds_read_b128 v[20:23], v0 offset:0
	v_mul_f32_e32 v13, v69, v13
	v_fmac_f32_e32 v10, v24, v56
	v_fmac_f32_e32 v11, v25, v56
	ds_read_b128 v[38:41], v0 offset:1024
	v_mul_f32_e32 v102, v42, v10
	v_fmac_f32_e32 v12, v26, v56
	v_fmac_f32_e32 v102, v43, v11
	s_waitcnt vmcnt(6)
	v_fmac_f32_e32 v13, v27, v56
	v_fmac_f32_e32 v102, v44, v12
	v_fmac_f32_e32 v102, v45, v13
	ds_read_b128 v[62:65], v0 offset:4608
	ds_write_b32 v107, v102 offset:12032
	ds_read_b32 v54, v1 offset:2048
	s_waitcnt lgkmcnt(12)
	v_mul_f32_e32 v10, v70, v10
	v_mul_f32_e32 v11, v71, v11
	v_mul_f32_e32 v12, v72, v12
	s_waitcnt lgkmcnt(10)
	v_mul_f32_e32 v13, v73, v13
	v_fmac_f32_e32 v10, v28, v58
	v_fmac_f32_e32 v11, v29, v58
	v_add_f32_e32 v114, v114, v118
	v_mul_f32_e32 v61, v46, v10
	v_fmac_f32_e32 v12, v30, v58
	v_fmac_f32_e32 v61, v47, v11
	v_add_f32_e32 v115, v115, v119
	v_fmac_f32_e32 v13, v31, v58
	v_fmac_f32_e32 v61, v48, v12
	v_fmac_f32_e32 v61, v49, v13
	v_add_f32_e32 v116, v116, v120
	ds_write_b32 v107, v61 offset:12288
	ds_read_b128 v[24:27], v0 offset:128
	ds_read_b128 v[42:45], v0 offset:1152
	ds_read_b128 v[66:69], v0 offset:4736
	ds_read_b32 v56, v1 offset:2080
	v_add_f32_e32 v117, v117, v121
	v_add_f32_e32 v114, v114, v115
	v_add_f32_e32 v116, v116, v117
	v_add_f32_e32 v114, v114, v116
	v_cvt_pk_bf16_f32 v19, v114, v114
	ds_write_b16 v105, v19 offset:13568
	s_waitcnt lgkmcnt(11)
	v_mul_f32_e32 v10, v74, v10
	v_mul_f32_e32 v11, v75, v11
	v_mul_f32_e32 v12, v76, v12
	ds_read_b128 v[28:31], v0 offset:256
	v_mul_f32_e32 v13, v77, v13
	v_fmac_f32_e32 v10, v32, v60
	v_fmac_f32_e32 v11, v33, v60
	ds_read_b128 v[46:49], v0 offset:1280
	v_mul_f32_e32 v102, v50, v10
	v_fmac_f32_e32 v12, v34, v60
	v_fmac_f32_e32 v102, v51, v11
	ds_read_b128 v[70:73], v0 offset:4864
	v_fmac_f32_e32 v13, v35, v60
	v_fmac_f32_e32 v102, v52, v12
	v_fmac_f32_e32 v102, v53, v13
	ds_read_b32 v58, v1 offset:2112
	ds_write_b32 v107, v102 offset:12544
	s_sub_u32 s12, s12, 1
	s_cmp_lg_u32 s12, 0
	s_cbranch_scc1 .Lls1_8_loop
	ds_read_b128 v[114:117], v112 offset:10752
	ds_read_b128 v[118:121], v113 offset:10752
	s_waitcnt lgkmcnt(0)
	v_add_f32_e32 v114, v114, v118
	v_add_f32_e32 v115, v115, v119
	v_add_f32_e32 v116, v116, v120
	v_add_f32_e32 v117, v117, v121
	v_add_f32_e32 v114, v114, v115
	v_add_f32_e32 v116, v116, v117
	v_add_f32_e32 v114, v114, v116
	v_cvt_pk_bf16_f32 v19, v114, v114
	ds_write_b16 v105, v19 offset:13696
	s_waitcnt lgkmcnt(0)
	ds_read_b128 v[108:111], v106 offset:13312
	s_waitcnt lgkmcnt(0)
	global_store_dwordx4 v7, v[108:111], s[94:95]
	v_add_u32_e32 v7, 0x20000, v7
	s_nop 0
	ds_read_b128 v[108:111], v106 offset:14336
	s_waitcnt lgkmcnt(0)
	global_store_dwordx4 v7, v[108:111], s[94:95]
	v_add_u32_e32 v7, 0x20000, v7
	s_nop 0
	ds_read_b128 v[108:111], v106 offset:15360
	s_waitcnt lgkmcnt(0)
	global_store_dwordx4 v7, v[108:111], s[94:95]
	v_add_u32_e32 v7, 0x20000, v7
	s_nop 0
	ds_read_b128 v[108:111], v106 offset:16384
	s_waitcnt lgkmcnt(0)
	global_store_dwordx4 v7, v[108:111], s[94:95]
	v_add_u32_e32 v7, 0x20000, v7
	s_nop 0
	ds_read_b128 v[108:111], v106 offset:17408
	s_waitcnt lgkmcnt(0)
	global_store_dwordx4 v7, v[108:111], s[94:95]
	v_add_u32_e32 v7, 0x20000, v7
	s_nop 0
	ds_read_b128 v[108:111], v106 offset:18432
	s_waitcnt lgkmcnt(0)
	global_store_dwordx4 v7, v[108:111], s[94:95]
	v_add_u32_e32 v7, 0x20000, v7
	s_nop 0
	ds_read_b128 v[108:111], v106 offset:19456
	s_waitcnt lgkmcnt(0)
	global_store_dwordx4 v7, v[108:111], s[94:95]
	v_add_u32_e32 v7, 0x20000, v7
	s_nop 0
	ds_read_b128 v[108:111], v106 offset:20480
	s_waitcnt lgkmcnt(0)
	global_store_dwordx4 v7, v[108:111], s[94:95]
	v_add_u32_e32 v7, 0x20000, v7
	s_nop 0
	global_store_dword v104, v10, s[26:27] offset:0
	global_store_dword v104, v11, s[26:27] offset:256
	global_store_dword v104, v12, s[26:27] offset:512
	global_store_dword v104, v13, s[26:27] offset:768
	s_waitcnt vmcnt(0) lgkmcnt(0)
	s_setprio 0
	s_branch .Lls_done
